# P5 GLU GEMM epilogue: y loads prefetched in one block (2 exposed round trips per tile instead of 16)
# baseline (speedup 1.0000x reference)
; template <bool SWAP, class Epi>
; DI void gemm_tile(const u16* __restrict__ Ag, long lda, const u16* __restrict__ Bg, long ldb, int ka0, int ka1, int kb0, int kb1, char* shm, Epi&& epi) {
;     ...
;   auto stage = [&](int buf, int kt) {
;     char* SA = shm + buf * 32768; char* SB = SA + 16384;
; #pragma unroll
;     for (int i = 0; i < 4; ++i) {
;       const int q = i * 256 + tid, r = q >> 3, c16 = (q & 7) ^ ((r >> 1) & 7);
;       __builtin_amdgcn_global_load_lds((const unsigned*)(Ag + (long)r * lda + kt * 64 + c16 * 8), (__attribute__((address_space(3))) unsigned*)(SA + q * 16), 16, 0, 0);
;       __builtin_amdgcn_global_load_lds((const unsigned*)(Bg + (long)r * ldb + kt * 64 + c16 * 8), (__attribute__((address_space(3))) unsigned*)(SB + q * 16), 16, 0, 0);
;     }
;   };
;   stage(0, ka0 < ka1 ? ka0 : kb0);
;   for (int i = 0; i < nk; ++i) {
;     asm volatile("s_waitcnt vmcnt(0)" ::: "memory");
;     __syncthreads();
;     if (i + 1 < nk) { const int j = i + 1; stage(j & 1, j < na ? ka0 + j : kb0 + (j - na)); }
;     const char* SA = shm + (i & 1) * 32768; const char* SB = SA + 16384;
; #pragma unroll
;     for (int ks = 0; ks < 2; ++ks) {
;       bf16x8 At[4], Bt[4];
; #pragma unroll
;       for (int m = 0; m < 4; ++m) {
;         const int ra = wr * 64 + m * 16 + fr, rb = wc * 64 + m * 16 + fr;
;         At[m] = *reinterpret_cast<const bf16x8*>(SA + ra * 128 + (((ks * 4 + fq) ^ ((ra >> 1) & 7)) * 16));
;         Bt[m] = *reinterpret_cast<const bf16x8*>(SB + rb * 128 + (((ks * 4 + fq) ^ ((rb >> 1) & 7)) * 16));
;       }
; #pragma unroll
;       for (int m = 0; m < 4; ++m)
; #pragma unroll
;         for (int n = 0; n < 4; ++n) acc[m][n] = SWAP ? __builtin_amdgcn_mfma_f32_16x16x32_bf16(Bt[n], At[m], acc[m][n], 0, 0, 0) : __builtin_amdgcn_mfma_f32_16x16x32_bf16(At[m], Bt[n], acc[m][n], 0, 0, 0);
.LBB0_874:
	v_add_u32_e32 v0, s18, v190
	v_cmp_gt_i32_e32 vcc, s8, v0
	v_mov_b32_e32 v1, s18
	v_mov_b32_e32 v123, v53
	v_cndmask_b32_e32 v0, v1, v0, vcc
	v_lshl_or_b32 v132, v0, 8, s9
	v_ashrrev_i32_e32 v133, 31, v132
	v_lshlrev_b64 v[0:1], 10, v[132:133]
	v_lshl_add_u64 v[6:7], s[54:55], 0, v[0:1]
	v_lshl_add_u64 v[0:1], v[6:7], 0, v[52:53]
	v_readfirstlane_b32 s26, v145
	v_add_u32_e32 v2, 0x4000, v145
	v_lshl_add_u64 v[0:1], v[0:1], 0, v[122:123]
	s_mov_b32 m0, s26
	v_readfirstlane_b32 s27, v2
	v_mov_b32_e32 v125, v53
	global_load_lds_dwordx4 v[0:1], off
	s_mov_b32 m0, s27
	v_lshl_add_u64 v[2:3], v[6:7], 0, v[124:125]
	v_readfirstlane_b32 s28, v146
	v_add_u32_e32 v4, 0x4000, v146
	global_load_lds_dwordx4 v[54:55], off
	v_lshl_add_u64 v[2:3], v[2:3], 0, v[122:123]
	s_mov_b32 m0, s28
	v_readfirstlane_b32 s29, v4
	v_mov_b32_e32 v127, v53
	global_load_lds_dwordx4 v[2:3], off
	s_mov_b32 m0, s29
	v_lshl_add_u64 v[4:5], v[6:7], 0, v[126:127]
	v_readfirstlane_b32 s30, v147
	v_add_u32_e32 v8, 0x4000, v147
	global_load_lds_dwordx4 v[56:57], off
	v_lshl_add_u64 v[4:5], v[4:5], 0, v[122:123]
	s_mov_b32 m0, s30
	v_readfirstlane_b32 s31, v8
	v_mov_b32_e32 v131, v53
	global_load_lds_dwordx4 v[4:5], off
	s_mov_b32 m0, s31
	v_lshl_add_u64 v[6:7], v[6:7], 0, v[130:131]
	v_readfirstlane_b32 s33, v148
	v_add_u32_e32 v8, 0x4000, v148
	global_load_lds_dwordx4 v[58:59], off
	v_lshl_add_u64 v[6:7], v[6:7], 0, v[122:123]
	s_mov_b32 m0, s33
	v_readfirstlane_b32 s34, v8
	v_add_u32_e32 v10, 0x8000, v145
	global_load_lds_dwordx4 v[6:7], off
	s_mov_b32 m0, s34
	v_readfirstlane_b32 s2, v10
	global_load_lds_dwordx4 v[60:61], off
	v_lshl_add_u64 v[8:9], v[0:1], 0, s[0:1]
	s_mov_b32 m0, s2
	s_waitcnt vmcnt(0)
	s_waitcnt vmcnt(0) lgkmcnt(0)
	s_barrier
	global_load_lds_dwordx4 v[8:9], off
	v_add_u32_e32 v8, 0xc000, v145
	v_add_u32_e32 v10, 0x8000, v146
	v_readfirstlane_b32 s19, v8
	s_mov_b32 m0, s19
	v_readfirstlane_b32 s20, v10
	global_load_lds_dwordx4 v[62:63], off
	v_lshl_add_u64 v[8:9], v[2:3], 0, s[0:1]
	s_mov_b32 m0, s20
	v_add_u32_e32 v10, 0x8000, v147
	global_load_lds_dwordx4 v[8:9], off
	v_add_u32_e32 v8, 0xc000, v146
	v_readfirstlane_b32 s22, v10
	v_readfirstlane_b32 s21, v8
	s_mov_b32 m0, s21
	v_lshl_add_u64 v[8:9], v[4:5], 0, s[0:1]
	global_load_lds_dwordx4 v[64:65], off
	s_mov_b32 m0, s22
	v_add_u32_e32 v10, 0x8000, v148
	global_load_lds_dwordx4 v[8:9], off
	v_add_u32_e32 v8, 0xc000, v147
	v_readfirstlane_b32 s24, v10
	v_readfirstlane_b32 s23, v8
	s_mov_b32 m0, s23
	v_lshl_add_u64 v[8:9], v[6:7], 0, s[0:1]
	global_load_lds_dwordx4 v[66:67], off
	s_mov_b32 m0, s24
	v_add_u32_e32 v10, v135, v139
	global_load_lds_dwordx4 v[8:9], off
	v_add_u32_e32 v8, 0xc000, v148
	v_add_u32_e32 v9, v135, v137
	v_readfirstlane_b32 s25, v8
	v_add_u32_e32 v8, v135, v136
	ds_read_b128 v[14:17], v8
	ds_read_b128 v[18:21], v9 offset:16384
	s_mov_b32 m0, s25
	v_add_u32_e32 v11, v135, v141
	global_load_lds_dwordx4 v[68:69], off
	v_add_u32_e32 v12, v135, v143
	ds_read_b128 v[22:25], v10
	ds_read_b128 v[26:29], v9 offset:18432
	ds_read_b128 v[30:33], v11
	ds_read_b128 v[34:37], v9 offset:20480
	ds_read_b128 v[38:41], v12
	ds_read_b128 v[42:45], v9 offset:22528
	s_waitcnt lgkmcnt(0)
	v_mfma_f32_16x16x32_bf16 v[46:49], v[18:21], v[14:17], 0
	v_add_u32_e32 v13, v144, v136
	v_lshl_add_u64 v[50:51], v[0:1], 0, s[4:5]
	s_mov_b32 m0, s26
	v_mfma_f32_16x16x32_bf16 v[150:153], v[26:29], v[14:17], 0
	s_add_i32 s18, s18, s65
	s_cmpk_lt_i32 s18, 0x80
	v_mfma_f32_16x16x32_bf16 v[154:157], v[34:37], v[14:17], 0
	v_mfma_f32_16x16x32_bf16 v[158:161], v[42:45], v[14:17], 0
	v_add_u32_e32 v14, v144, v137
	ds_read_b128 v[210:213], v14 offset:16384
	v_add_u32_e32 v15, v144, v139
	v_mfma_f32_16x16x32_bf16 v[162:165], v[18:21], v[22:25], 0
	v_add_u32_e32 v16, v144, v141
	v_add_u32_e32 v17, v144, v143
	v_mfma_f32_16x16x32_bf16 v[176:179], v[26:29], v[22:25], 0
	v_mfma_f32_16x16x32_bf16 v[180:183], v[34:37], v[22:25], 0
	v_mfma_f32_16x16x32_bf16 v[22:25], v[42:45], v[22:25], 0
	v_mfma_f32_16x16x32_bf16 v[184:187], v[18:21], v[30:33], 0
	v_mfma_f32_16x16x32_bf16 v[198:201], v[26:29], v[30:33], 0
	v_mfma_f32_16x16x32_bf16 v[202:205], v[34:37], v[30:33], 0
	v_mfma_f32_16x16x32_bf16 v[30:33], v[42:45], v[30:33], 0
	v_mfma_f32_16x16x32_bf16 v[18:21], v[18:21], v[38:41], 0
	v_mfma_f32_16x16x32_bf16 v[26:29], v[26:29], v[38:41], 0
	v_mfma_f32_16x16x32_bf16 v[34:37], v[34:37], v[38:41], 0
	v_mfma_f32_16x16x32_bf16 v[38:41], v[42:45], v[38:41], 0
	ds_read_b128 v[42:45], v13
	ds_read_b128 v[214:217], v15
	ds_read_b128 v[218:221], v14 offset:18432
	ds_read_b128 v[222:225], v16
	ds_read_b128 v[226:229], v14 offset:20480
	ds_read_b128 v[230:233], v17
	ds_read_b128 v[234:237], v14 offset:22528
	s_waitcnt vmcnt(0)
	s_waitcnt vmcnt(0) lgkmcnt(0)
	s_barrier
; template <bool SWAP, class Epi>
; DI void gemm_tile(const u16* __restrict__ Ag, long lda, const u16* __restrict__ Bg, long ldb, int ka0, int ka1, int kb0, int kb1, char* shm, Epi&& epi) {
;     ...
;   for (int i = 0; i < nk; ++i) {
;     asm volatile("s_waitcnt vmcnt(0)" ::: "memory");
;     __syncthreads();
;     if (i + 1 < nk) { const int j = i + 1; stage(j & 1, j < na ? ka0 + j : kb0 + (j - na)); }
;     const char* SA = shm + (i & 1) * 32768; const char* SB = SA + 16384;
; #pragma unroll
;     for (int ks = 0; ks < 2; ++ks) {
;       bf16x8 At[4], Bt[4];
; #pragma unroll
;       for (int m = 0; m < 4; ++m) {
;         const int ra = wr * 64 + m * 16 + fr, rb = wc * 64 + m * 16 + fr;
;         At[m] = *reinterpret_cast<const bf16x8*>(SA + ra * 128 + (((ks * 4 + fq) ^ ((ra >> 1) & 7)) * 16));
;         Bt[m] = *reinterpret_cast<const bf16x8*>(SB + rb * 128 + (((ks * 4 + fq) ^ ((rb >> 1) & 7)) * 16));
;       }
; #pragma unroll
;       for (int m = 0; m < 4; ++m)
; #pragma unroll
;         for (int n = 0; n < 4; ++n) acc[m][n] = SWAP ? __builtin_amdgcn_mfma_f32_16x16x32_bf16(Bt[n], At[m], acc[m][n], 0, 0, 0) : __builtin_amdgcn_mfma_f32_16x16x32_bf16(At[m], Bt[n], acc[m][n], 0, 0, 0);
	global_load_lds_dwordx4 v[50:51], off
	s_mov_b32 m0, s27
	v_lshl_add_u64 v[50:51], v[2:3], 0, s[4:5]
	global_load_lds_dwordx4 v[70:71], off
	s_mov_b32 m0, s28
	v_mfma_f32_16x16x32_bf16 v[46:49], v[210:213], v[42:45], v[46:49]
	global_load_lds_dwordx4 v[50:51], off
	s_mov_b32 m0, s29
	v_lshl_add_u64 v[50:51], v[4:5], 0, s[4:5]
	global_load_lds_dwordx4 v[72:73], off
	s_mov_b32 m0, s30
	v_mfma_f32_16x16x32_bf16 v[150:153], v[218:221], v[42:45], v[150:153]
	global_load_lds_dwordx4 v[50:51], off
	s_mov_b32 m0, s31
	v_lshl_add_u64 v[50:51], v[6:7], 0, s[4:5]
	global_load_lds_dwordx4 v[74:75], off
	s_mov_b32 m0, s33
	v_mfma_f32_16x16x32_bf16 v[154:157], v[226:229], v[42:45], v[154:157]
	global_load_lds_dwordx4 v[50:51], off
	s_mov_b32 m0, s34
	v_mfma_f32_16x16x32_bf16 v[42:45], v[234:237], v[42:45], v[158:161]
	global_load_lds_dwordx4 v[76:77], off
	v_lshl_add_u64 v[50:51], v[0:1], 0, s[6:7]
	v_mfma_f32_16x16x32_bf16 v[158:161], v[210:213], v[214:217], v[162:165]
	s_mov_b32 m0, s2
	v_mfma_f32_16x16x32_bf16 v[162:165], v[218:221], v[214:217], v[176:179]
	v_mfma_f32_16x16x32_bf16 v[176:179], v[226:229], v[214:217], v[180:183]
	v_mfma_f32_16x16x32_bf16 v[22:25], v[234:237], v[214:217], v[22:25]
	v_mfma_f32_16x16x32_bf16 v[180:183], v[210:213], v[222:225], v[184:187]
	v_mfma_f32_16x16x32_bf16 v[184:187], v[218:221], v[222:225], v[198:201]
	v_mfma_f32_16x16x32_bf16 v[198:201], v[226:229], v[222:225], v[202:205]
	v_mfma_f32_16x16x32_bf16 v[30:33], v[234:237], v[222:225], v[30:33]
	v_mfma_f32_16x16x32_bf16 v[18:21], v[210:213], v[230:233], v[18:21]
	v_mfma_f32_16x16x32_bf16 v[26:29], v[218:221], v[230:233], v[26:29]
	v_mfma_f32_16x16x32_bf16 v[34:37], v[226:229], v[230:233], v[34:37]
	v_mfma_f32_16x16x32_bf16 v[38:41], v[234:237], v[230:233], v[38:41]
	ds_read_b128 v[202:205], v8 offset:32768
	ds_read_b128 v[210:213], v9 offset:49152
	ds_read_b128 v[214:217], v10 offset:32768
	ds_read_b128 v[218:221], v9 offset:51200
	ds_read_b128 v[222:225], v11 offset:32768
	ds_read_b128 v[226:229], v9 offset:53248
	ds_read_b128 v[230:233], v12 offset:32768
	ds_read_b128 v[234:237], v9 offset:55296
	s_waitcnt lgkmcnt(0)
	v_mfma_f32_16x16x32_bf16 v[46:49], v[210:213], v[202:205], v[46:49]
	v_mfma_f32_16x16x32_bf16 v[150:153], v[218:221], v[202:205], v[150:153]
	v_mfma_f32_16x16x32_bf16 v[154:157], v[226:229], v[202:205], v[154:157]
	v_mfma_f32_16x16x32_bf16 v[42:45], v[234:237], v[202:205], v[42:45]
	v_mfma_f32_16x16x32_bf16 v[158:161], v[210:213], v[214:217], v[158:161]
	v_mfma_f32_16x16x32_bf16 v[162:165], v[218:221], v[214:217], v[162:165]
	v_mfma_f32_16x16x32_bf16 v[176:179], v[226:229], v[214:217], v[176:179]
	v_mfma_f32_16x16x32_bf16 v[22:25], v[234:237], v[214:217], v[22:25]
	v_mfma_f32_16x16x32_bf16 v[180:183], v[210:213], v[222:225], v[180:183]
	v_mfma_f32_16x16x32_bf16 v[184:187], v[218:221], v[222:225], v[184:187]
	v_mfma_f32_16x16x32_bf16 v[198:201], v[226:229], v[222:225], v[198:201]
	v_mfma_f32_16x16x32_bf16 v[30:33], v[234:237], v[222:225], v[30:33]
	v_mfma_f32_16x16x32_bf16 v[18:21], v[210:213], v[230:233], v[18:21]
	v_mfma_f32_16x16x32_bf16 v[26:29], v[218:221], v[230:233], v[26:29]
	v_mfma_f32_16x16x32_bf16 v[34:37], v[226:229], v[230:233], v[34:37]
	v_mfma_f32_16x16x32_bf16 v[38:41], v[234:237], v[230:233], v[38:41]
	ds_read_b128 v[202:205], v13 offset:32768
	ds_read_b128 v[210:213], v14 offset:49152
	ds_read_b128 v[214:217], v15 offset:32768
	ds_read_b128 v[218:221], v14 offset:51200
	ds_read_b128 v[222:225], v16 offset:32768
	ds_read_b128 v[226:229], v14 offset:53248
	ds_read_b128 v[230:233], v17 offset:32768
	ds_read_b128 v[234:237], v14 offset:55296
	s_waitcnt vmcnt(0)
	s_waitcnt vmcnt(0) lgkmcnt(0)
	s_barrier
	global_load_lds_dwordx4 v[50:51], off
	s_mov_b32 m0, s19
	v_lshl_add_u64 v[50:51], v[2:3], 0, s[6:7]
	global_load_lds_dwordx4 v[78:79], off
	s_mov_b32 m0, s20
	v_mfma_f32_16x16x32_bf16 v[46:49], v[210:213], v[202:205], v[46:49]
	global_load_lds_dwordx4 v[50:51], off
	s_mov_b32 m0, s21
	v_lshl_add_u64 v[50:51], v[4:5], 0, s[6:7]
	global_load_lds_dwordx4 v[80:81], off
	s_mov_b32 m0, s22
	v_mfma_f32_16x16x32_bf16 v[150:153], v[218:221], v[202:205], v[150:153]
	global_load_lds_dwordx4 v[50:51], off
	s_mov_b32 m0, s23
	v_lshl_add_u64 v[50:51], v[6:7], 0, s[6:7]
	global_load_lds_dwordx4 v[82:83], off
	s_mov_b32 m0, s24
	v_mfma_f32_16x16x32_bf16 v[154:157], v[226:229], v[202:205], v[154:157]
	global_load_lds_dwordx4 v[50:51], off
	s_mov_b32 m0, s25
	v_mfma_f32_16x16x32_bf16 v[42:45], v[234:237], v[202:205], v[42:45]
	global_load_lds_dwordx4 v[84:85], off
	v_lshl_add_u64 v[50:51], v[0:1], 0, s[10:11]
	v_mfma_f32_16x16x32_bf16 v[158:161], v[210:213], v[214:217], v[158:161]
	s_mov_b32 m0, s26
	v_mfma_f32_16x16x32_bf16 v[162:165], v[218:221], v[214:217], v[162:165]
	v_mfma_f32_16x16x32_bf16 v[176:179], v[226:229], v[214:217], v[176:179]
	v_mfma_f32_16x16x32_bf16 v[22:25], v[234:237], v[214:217], v[22:25]
	v_mfma_f32_16x16x32_bf16 v[180:183], v[210:213], v[222:225], v[180:183]
	v_mfma_f32_16x16x32_bf16 v[184:187], v[218:221], v[222:225], v[184:187]
	v_mfma_f32_16x16x32_bf16 v[198:201], v[226:229], v[222:225], v[198:201]
	v_mfma_f32_16x16x32_bf16 v[30:33], v[234:237], v[222:225], v[30:33]
	v_mfma_f32_16x16x32_bf16 v[18:21], v[210:213], v[230:233], v[18:21]
	v_mfma_f32_16x16x32_bf16 v[26:29], v[218:221], v[230:233], v[26:29]
	v_mfma_f32_16x16x32_bf16 v[34:37], v[226:229], v[230:233], v[34:37]
	v_mfma_f32_16x16x32_bf16 v[38:41], v[234:237], v[230:233], v[38:41]
	ds_read_b128 v[202:205], v8
	ds_read_b128 v[210:213], v9 offset:16384
	ds_read_b128 v[214:217], v10
	ds_read_b128 v[218:221], v9 offset:18432
	ds_read_b128 v[222:225], v11
	ds_read_b128 v[226:229], v9 offset:20480
	ds_read_b128 v[230:233], v12
	ds_read_b128 v[234:237], v9 offset:22528
	s_waitcnt lgkmcnt(0)
; template <bool SWAP, class Epi>
; DI void gemm_tile(const u16* __restrict__ Ag, long lda, const u16* __restrict__ Bg, long ldb, int ka0, int ka1, int kb0, int kb1, char* shm, Epi&& epi) {
;     ...
;   for (int i = 0; i < nk; ++i) {
;     asm volatile("s_waitcnt vmcnt(0)" ::: "memory");
;     __syncthreads();
;     if (i + 1 < nk) { const int j = i + 1; stage(j & 1, j < na ? ka0 + j : kb0 + (j - na)); }
;     const char* SA = shm + (i & 1) * 32768; const char* SB = SA + 16384;
; #pragma unroll
;     for (int ks = 0; ks < 2; ++ks) {
;       bf16x8 At[4], Bt[4];
; #pragma unroll
;       for (int m = 0; m < 4; ++m) {
;         const int ra = wr * 64 + m * 16 + fr, rb = wc * 64 + m * 16 + fr;
;         At[m] = *reinterpret_cast<const bf16x8*>(SA + ra * 128 + (((ks * 4 + fq) ^ ((ra >> 1) & 7)) * 16));
;         Bt[m] = *reinterpret_cast<const bf16x8*>(SB + rb * 128 + (((ks * 4 + fq) ^ ((rb >> 1) & 7)) * 16));
;       }
; #pragma unroll
;       for (int m = 0; m < 4; ++m)
; #pragma unroll
;         for (int n = 0; n < 4; ++n) acc[m][n] = SWAP ? __builtin_amdgcn_mfma_f32_16x16x32_bf16(Bt[n], At[m], acc[m][n], 0, 0, 0) : __builtin_amdgcn_mfma_f32_16x16x32_bf16(At[m], Bt[n], acc[m][n], 0, 0, 0);
	v_mfma_f32_16x16x32_bf16 v[46:49], v[210:213], v[202:205], v[46:49]
	v_mfma_f32_16x16x32_bf16 v[150:153], v[218:221], v[202:205], v[150:153]
	v_mfma_f32_16x16x32_bf16 v[154:157], v[226:229], v[202:205], v[154:157]
	v_mfma_f32_16x16x32_bf16 v[42:45], v[234:237], v[202:205], v[42:45]
	v_mfma_f32_16x16x32_bf16 v[158:161], v[210:213], v[214:217], v[158:161]
	v_mfma_f32_16x16x32_bf16 v[162:165], v[218:221], v[214:217], v[162:165]
	v_mfma_f32_16x16x32_bf16 v[176:179], v[226:229], v[214:217], v[176:179]
	v_mfma_f32_16x16x32_bf16 v[22:25], v[234:237], v[214:217], v[22:25]
	v_mfma_f32_16x16x32_bf16 v[180:183], v[210:213], v[222:225], v[180:183]
	v_mfma_f32_16x16x32_bf16 v[184:187], v[218:221], v[222:225], v[184:187]
	v_mfma_f32_16x16x32_bf16 v[198:201], v[226:229], v[222:225], v[198:201]
	v_mfma_f32_16x16x32_bf16 v[30:33], v[234:237], v[222:225], v[30:33]
	v_mfma_f32_16x16x32_bf16 v[18:21], v[210:213], v[230:233], v[18:21]
	v_mfma_f32_16x16x32_bf16 v[26:29], v[218:221], v[230:233], v[26:29]
	v_mfma_f32_16x16x32_bf16 v[34:37], v[226:229], v[230:233], v[34:37]
	v_mfma_f32_16x16x32_bf16 v[38:41], v[234:237], v[230:233], v[38:41]
	ds_read_b128 v[202:205], v13
	ds_read_b128 v[210:213], v14 offset:16384
	ds_read_b128 v[214:217], v15
	ds_read_b128 v[218:221], v14 offset:18432
	ds_read_b128 v[222:225], v16
	ds_read_b128 v[226:229], v14 offset:20480
	ds_read_b128 v[230:233], v17
	ds_read_b128 v[234:237], v14 offset:22528
	s_waitcnt vmcnt(0)
	s_waitcnt vmcnt(0) lgkmcnt(0)
	s_barrier
	global_load_lds_dwordx4 v[50:51], off
	s_mov_b32 m0, s27
	v_lshl_add_u64 v[50:51], v[2:3], 0, s[10:11]
	global_load_lds_dwordx4 v[86:87], off
	s_mov_b32 m0, s28
	v_mfma_f32_16x16x32_bf16 v[46:49], v[210:213], v[202:205], v[46:49]
	global_load_lds_dwordx4 v[50:51], off
	s_mov_b32 m0, s29
	v_lshl_add_u64 v[50:51], v[4:5], 0, s[10:11]
	global_load_lds_dwordx4 v[88:89], off
	s_mov_b32 m0, s30
	v_mfma_f32_16x16x32_bf16 v[150:153], v[218:221], v[202:205], v[150:153]
	global_load_lds_dwordx4 v[50:51], off
	s_mov_b32 m0, s31
	v_lshl_add_u64 v[50:51], v[6:7], 0, s[10:11]
	global_load_lds_dwordx4 v[90:91], off
	s_mov_b32 m0, s33
	v_mfma_f32_16x16x32_bf16 v[154:157], v[226:229], v[202:205], v[154:157]
	global_load_lds_dwordx4 v[50:51], off
	s_mov_b32 m0, s34
	v_mfma_f32_16x16x32_bf16 v[42:45], v[234:237], v[202:205], v[42:45]
	global_load_lds_dwordx4 v[92:93], off
	v_lshl_add_u64 v[50:51], v[0:1], 0, s[12:13]
	v_mfma_f32_16x16x32_bf16 v[158:161], v[210:213], v[214:217], v[158:161]
	s_mov_b32 m0, s2
	v_mfma_f32_16x16x32_bf16 v[162:165], v[218:221], v[214:217], v[162:165]
	v_mfma_f32_16x16x32_bf16 v[176:179], v[226:229], v[214:217], v[176:179]
	v_mfma_f32_16x16x32_bf16 v[22:25], v[234:237], v[214:217], v[22:25]
	v_mfma_f32_16x16x32_bf16 v[180:183], v[210:213], v[222:225], v[180:183]
	v_mfma_f32_16x16x32_bf16 v[184:187], v[218:221], v[222:225], v[184:187]
	v_mfma_f32_16x16x32_bf16 v[198:201], v[226:229], v[222:225], v[198:201]
	v_mfma_f32_16x16x32_bf16 v[30:33], v[234:237], v[222:225], v[30:33]
	v_mfma_f32_16x16x32_bf16 v[18:21], v[210:213], v[230:233], v[18:21]
	v_mfma_f32_16x16x32_bf16 v[26:29], v[218:221], v[230:233], v[26:29]
	v_mfma_f32_16x16x32_bf16 v[34:37], v[226:229], v[230:233], v[34:37]
	v_mfma_f32_16x16x32_bf16 v[38:41], v[234:237], v[230:233], v[38:41]
	ds_read_b128 v[202:205], v8 offset:32768
	ds_read_b128 v[210:213], v9 offset:49152
	ds_read_b128 v[214:217], v10 offset:32768
	ds_read_b128 v[218:221], v9 offset:51200
	ds_read_b128 v[222:225], v11 offset:32768
	ds_read_b128 v[226:229], v9 offset:53248
	ds_read_b128 v[230:233], v12 offset:32768
	ds_read_b128 v[234:237], v9 offset:55296
	s_waitcnt lgkmcnt(0)
	v_mfma_f32_16x16x32_bf16 v[46:49], v[210:213], v[202:205], v[46:49]
	v_mfma_f32_16x16x32_bf16 v[150:153], v[218:221], v[202:205], v[150:153]
	v_mfma_f32_16x16x32_bf16 v[154:157], v[226:229], v[202:205], v[154:157]
	v_mfma_f32_16x16x32_bf16 v[42:45], v[234:237], v[202:205], v[42:45]
	v_mfma_f32_16x16x32_bf16 v[158:161], v[210:213], v[214:217], v[158:161]
	v_mfma_f32_16x16x32_bf16 v[162:165], v[218:221], v[214:217], v[162:165]
	v_mfma_f32_16x16x32_bf16 v[176:179], v[226:229], v[214:217], v[176:179]
	v_mfma_f32_16x16x32_bf16 v[22:25], v[234:237], v[214:217], v[22:25]
	v_mfma_f32_16x16x32_bf16 v[180:183], v[210:213], v[222:225], v[180:183]
	v_mfma_f32_16x16x32_bf16 v[184:187], v[218:221], v[222:225], v[184:187]
	v_mfma_f32_16x16x32_bf16 v[198:201], v[226:229], v[222:225], v[198:201]
	v_mfma_f32_16x16x32_bf16 v[30:33], v[234:237], v[222:225], v[30:33]
	v_mfma_f32_16x16x32_bf16 v[18:21], v[210:213], v[230:233], v[18:21]
	v_mfma_f32_16x16x32_bf16 v[26:29], v[218:221], v[230:233], v[26:29]
	v_mfma_f32_16x16x32_bf16 v[34:37], v[226:229], v[230:233], v[34:37]
	v_mfma_f32_16x16x32_bf16 v[38:41], v[234:237], v[230:233], v[38:41]
	ds_read_b128 v[202:205], v13 offset:32768
	ds_read_b128 v[210:213], v14 offset:49152
	ds_read_b128 v[214:217], v15 offset:32768
	ds_read_b128 v[218:221], v14 offset:51200
	ds_read_b128 v[222:225], v16 offset:32768
	ds_read_b128 v[226:229], v14 offset:53248
	ds_read_b128 v[230:233], v17 offset:32768
	ds_read_b128 v[234:237], v14 offset:55296
	s_waitcnt vmcnt(0)
	s_waitcnt vmcnt(0) lgkmcnt(0)
	s_barrier
; template <bool SWAP, class Epi>
; DI void gemm_tile(const u16* __restrict__ Ag, long lda, const u16* __restrict__ Bg, long ldb, int ka0, int ka1, int kb0, int kb1, char* shm, Epi&& epi) {
;     ...
;   for (int i = 0; i < nk; ++i) {
;     asm volatile("s_waitcnt vmcnt(0)" ::: "memory");
;     __syncthreads();
;     if (i + 1 < nk) { const int j = i + 1; stage(j & 1, j < na ? ka0 + j : kb0 + (j - na)); }
;     const char* SA = shm + (i & 1) * 32768; const char* SB = SA + 16384;
; #pragma unroll
;     for (int ks = 0; ks < 2; ++ks) {
;       bf16x8 At[4], Bt[4];
; #pragma unroll
;       for (int m = 0; m < 4; ++m) {
;         const int ra = wr * 64 + m * 16 + fr, rb = wc * 64 + m * 16 + fr;
;         At[m] = *reinterpret_cast<const bf16x8*>(SA + ra * 128 + (((ks * 4 + fq) ^ ((ra >> 1) & 7)) * 16));
;         Bt[m] = *reinterpret_cast<const bf16x8*>(SB + rb * 128 + (((ks * 4 + fq) ^ ((rb >> 1) & 7)) * 16));
;       }
; #pragma unroll
;       for (int m = 0; m < 4; ++m)
; #pragma unroll
;         for (int n = 0; n < 4; ++n) acc[m][n] = SWAP ? __builtin_amdgcn_mfma_f32_16x16x32_bf16(Bt[n], At[m], acc[m][n], 0, 0, 0) : __builtin_amdgcn_mfma_f32_16x16x32_bf16(At[m], Bt[n], acc[m][n], 0, 0, 0);
	global_load_lds_dwordx4 v[50:51], off
	s_mov_b32 m0, s19
	v_lshl_add_u64 v[50:51], v[2:3], 0, s[12:13]
	global_load_lds_dwordx4 v[94:95], off
	s_mov_b32 m0, s20
	v_mfma_f32_16x16x32_bf16 v[46:49], v[210:213], v[202:205], v[46:49]
	global_load_lds_dwordx4 v[50:51], off
	s_mov_b32 m0, s21
	v_lshl_add_u64 v[50:51], v[4:5], 0, s[12:13]
	global_load_lds_dwordx4 v[96:97], off
	s_mov_b32 m0, s22
	v_mfma_f32_16x16x32_bf16 v[150:153], v[218:221], v[202:205], v[150:153]
	global_load_lds_dwordx4 v[50:51], off
	s_mov_b32 m0, s23
	v_lshl_add_u64 v[50:51], v[6:7], 0, s[12:13]
	global_load_lds_dwordx4 v[98:99], off
	s_mov_b32 m0, s24
	v_mfma_f32_16x16x32_bf16 v[154:157], v[226:229], v[202:205], v[154:157]
	global_load_lds_dwordx4 v[50:51], off
	s_mov_b32 m0, s25
	v_mfma_f32_16x16x32_bf16 v[42:45], v[234:237], v[202:205], v[42:45]
	global_load_lds_dwordx4 v[100:101], off
	v_lshl_add_u64 v[50:51], v[0:1], 0, s[14:15]
	v_mfma_f32_16x16x32_bf16 v[158:161], v[210:213], v[214:217], v[158:161]
	s_mov_b32 m0, s26
	v_lshl_add_u64 v[0:1], v[0:1], 0, s[16:17]
	v_mfma_f32_16x16x32_bf16 v[162:165], v[218:221], v[214:217], v[162:165]
	v_mfma_f32_16x16x32_bf16 v[176:179], v[226:229], v[214:217], v[176:179]
	v_mfma_f32_16x16x32_bf16 v[22:25], v[234:237], v[214:217], v[22:25]
	v_mfma_f32_16x16x32_bf16 v[180:183], v[210:213], v[222:225], v[180:183]
	v_mfma_f32_16x16x32_bf16 v[184:187], v[218:221], v[222:225], v[184:187]
	v_mfma_f32_16x16x32_bf16 v[198:201], v[226:229], v[222:225], v[198:201]
	v_mfma_f32_16x16x32_bf16 v[30:33], v[234:237], v[222:225], v[30:33]
	v_mfma_f32_16x16x32_bf16 v[18:21], v[210:213], v[230:233], v[18:21]
	v_mfma_f32_16x16x32_bf16 v[26:29], v[218:221], v[230:233], v[26:29]
	v_mfma_f32_16x16x32_bf16 v[34:37], v[226:229], v[230:233], v[34:37]
	v_mfma_f32_16x16x32_bf16 v[38:41], v[234:237], v[230:233], v[38:41]
	ds_read_b128 v[202:205], v8
	ds_read_b128 v[210:213], v9 offset:16384
	ds_read_b128 v[214:217], v10
	ds_read_b128 v[218:221], v9 offset:18432
	ds_read_b128 v[222:225], v11
	ds_read_b128 v[226:229], v9 offset:20480
	ds_read_b128 v[230:233], v12
	ds_read_b128 v[234:237], v9 offset:22528
	s_waitcnt lgkmcnt(0)
	v_mfma_f32_16x16x32_bf16 v[46:49], v[210:213], v[202:205], v[46:49]
	v_mfma_f32_16x16x32_bf16 v[150:153], v[218:221], v[202:205], v[150:153]
	v_mfma_f32_16x16x32_bf16 v[154:157], v[226:229], v[202:205], v[154:157]
	v_mfma_f32_16x16x32_bf16 v[42:45], v[234:237], v[202:205], v[42:45]
	v_mfma_f32_16x16x32_bf16 v[158:161], v[210:213], v[214:217], v[158:161]
	v_mfma_f32_16x16x32_bf16 v[162:165], v[218:221], v[214:217], v[162:165]
	v_mfma_f32_16x16x32_bf16 v[176:179], v[226:229], v[214:217], v[176:179]
	v_mfma_f32_16x16x32_bf16 v[22:25], v[234:237], v[214:217], v[22:25]
	v_mfma_f32_16x16x32_bf16 v[180:183], v[210:213], v[222:225], v[180:183]
	v_mfma_f32_16x16x32_bf16 v[184:187], v[218:221], v[222:225], v[184:187]
	v_mfma_f32_16x16x32_bf16 v[198:201], v[226:229], v[222:225], v[198:201]
	v_mfma_f32_16x16x32_bf16 v[30:33], v[234:237], v[222:225], v[30:33]
	v_mfma_f32_16x16x32_bf16 v[18:21], v[210:213], v[230:233], v[18:21]
	v_mfma_f32_16x16x32_bf16 v[26:29], v[218:221], v[230:233], v[26:29]
	v_mfma_f32_16x16x32_bf16 v[34:37], v[226:229], v[230:233], v[34:37]
	v_mfma_f32_16x16x32_bf16 v[38:41], v[234:237], v[230:233], v[38:41]
	ds_read_b128 v[202:205], v13
	ds_read_b128 v[210:213], v14 offset:16384
	ds_read_b128 v[214:217], v15
	ds_read_b128 v[218:221], v14 offset:18432
	ds_read_b128 v[222:225], v16
	ds_read_b128 v[226:229], v14 offset:20480
	ds_read_b128 v[230:233], v17
	ds_read_b128 v[234:237], v14 offset:22528
	s_waitcnt vmcnt(0)
	s_waitcnt vmcnt(0) lgkmcnt(0)
	s_barrier
	global_load_lds_dwordx4 v[50:51], off
	s_mov_b32 m0, s27
	v_lshl_add_u64 v[50:51], v[2:3], 0, s[14:15]
	global_load_lds_dwordx4 v[102:103], off
	s_mov_b32 m0, s28
	v_mfma_f32_16x16x32_bf16 v[46:49], v[210:213], v[202:205], v[46:49]
	global_load_lds_dwordx4 v[50:51], off
	s_mov_b32 m0, s29
	v_lshl_add_u64 v[50:51], v[4:5], 0, s[14:15]
	global_load_lds_dwordx4 v[104:105], off
	s_mov_b32 m0, s30
	v_mfma_f32_16x16x32_bf16 v[150:153], v[218:221], v[202:205], v[150:153]
	global_load_lds_dwordx4 v[50:51], off
	s_mov_b32 m0, s31
	v_lshl_add_u64 v[50:51], v[6:7], 0, s[14:15]
	global_load_lds_dwordx4 v[106:107], off
	s_mov_b32 m0, s33
	v_mfma_f32_16x16x32_bf16 v[154:157], v[226:229], v[202:205], v[154:157]
	global_load_lds_dwordx4 v[50:51], off
	s_mov_b32 m0, s34
	v_mfma_f32_16x16x32_bf16 v[42:45], v[234:237], v[202:205], v[42:45]
	global_load_lds_dwordx4 v[108:109], off
	s_mov_b32 m0, s2
	v_mfma_f32_16x16x32_bf16 v[158:161], v[210:213], v[214:217], v[158:161]
	v_mfma_f32_16x16x32_bf16 v[162:165], v[218:221], v[214:217], v[162:165]
	v_mfma_f32_16x16x32_bf16 v[176:179], v[226:229], v[214:217], v[176:179]
	v_mfma_f32_16x16x32_bf16 v[22:25], v[234:237], v[214:217], v[22:25]
	v_mfma_f32_16x16x32_bf16 v[180:183], v[210:213], v[222:225], v[180:183]
	v_mfma_f32_16x16x32_bf16 v[184:187], v[218:221], v[222:225], v[184:187]
	v_mfma_f32_16x16x32_bf16 v[198:201], v[226:229], v[222:225], v[198:201]
	v_mfma_f32_16x16x32_bf16 v[30:33], v[234:237], v[222:225], v[30:33]
	v_mfma_f32_16x16x32_bf16 v[18:21], v[210:213], v[230:233], v[18:21]
	v_mfma_f32_16x16x32_bf16 v[26:29], v[218:221], v[230:233], v[26:29]
	v_mfma_f32_16x16x32_bf16 v[34:37], v[226:229], v[230:233], v[34:37]
	v_mfma_f32_16x16x32_bf16 v[38:41], v[234:237], v[230:233], v[38:41]
	ds_read_b128 v[202:205], v8 offset:32768
	ds_read_b128 v[210:213], v9 offset:49152
	ds_read_b128 v[214:217], v10 offset:32768
	ds_read_b128 v[218:221], v9 offset:51200
	ds_read_b128 v[222:225], v11 offset:32768
	ds_read_b128 v[226:229], v9 offset:53248
	ds_read_b128 v[230:233], v12 offset:32768
	ds_read_b128 v[234:237], v9 offset:55296
	s_waitcnt lgkmcnt(0)
; template <bool SWAP, class Epi>
; DI void gemm_tile(const u16* __restrict__ Ag, long lda, const u16* __restrict__ Bg, long ldb, int ka0, int ka1, int kb0, int kb1, char* shm, Epi&& epi) {
;     ...
;   for (int i = 0; i < nk; ++i) {
;     asm volatile("s_waitcnt vmcnt(0)" ::: "memory");
;     __syncthreads();
;     if (i + 1 < nk) { const int j = i + 1; stage(j & 1, j < na ? ka0 + j : kb0 + (j - na)); }
;     const char* SA = shm + (i & 1) * 32768; const char* SB = SA + 16384;
; #pragma unroll
;     for (int ks = 0; ks < 2; ++ks) {
;       bf16x8 At[4], Bt[4];
; #pragma unroll
;       for (int m = 0; m < 4; ++m) {
;         const int ra = wr * 64 + m * 16 + fr, rb = wc * 64 + m * 16 + fr;
;         At[m] = *reinterpret_cast<const bf16x8*>(SA + ra * 128 + (((ks * 4 + fq) ^ ((ra >> 1) & 7)) * 16));
;         Bt[m] = *reinterpret_cast<const bf16x8*>(SB + rb * 128 + (((ks * 4 + fq) ^ ((rb >> 1) & 7)) * 16));
;       }
; #pragma unroll
;       for (int m = 0; m < 4; ++m)
; #pragma unroll
;         for (int n = 0; n < 4; ++n) acc[m][n] = SWAP ? __builtin_amdgcn_mfma_f32_16x16x32_bf16(Bt[n], At[m], acc[m][n], 0, 0, 0) : __builtin_amdgcn_mfma_f32_16x16x32_bf16(At[m], Bt[n], acc[m][n], 0, 0, 0);
	v_mfma_f32_16x16x32_bf16 v[46:49], v[210:213], v[202:205], v[46:49]
	v_mfma_f32_16x16x32_bf16 v[150:153], v[218:221], v[202:205], v[150:153]
	v_mfma_f32_16x16x32_bf16 v[154:157], v[226:229], v[202:205], v[154:157]
	v_mfma_f32_16x16x32_bf16 v[42:45], v[234:237], v[202:205], v[42:45]
	v_mfma_f32_16x16x32_bf16 v[158:161], v[210:213], v[214:217], v[158:161]
	v_mfma_f32_16x16x32_bf16 v[162:165], v[218:221], v[214:217], v[162:165]
	v_mfma_f32_16x16x32_bf16 v[176:179], v[226:229], v[214:217], v[176:179]
	v_mfma_f32_16x16x32_bf16 v[22:25], v[234:237], v[214:217], v[22:25]
	v_mfma_f32_16x16x32_bf16 v[180:183], v[210:213], v[222:225], v[180:183]
	v_mfma_f32_16x16x32_bf16 v[184:187], v[218:221], v[222:225], v[184:187]
	v_mfma_f32_16x16x32_bf16 v[198:201], v[226:229], v[222:225], v[198:201]
	v_mfma_f32_16x16x32_bf16 v[30:33], v[234:237], v[222:225], v[30:33]
	v_mfma_f32_16x16x32_bf16 v[18:21], v[210:213], v[230:233], v[18:21]
	v_mfma_f32_16x16x32_bf16 v[26:29], v[218:221], v[230:233], v[26:29]
	v_mfma_f32_16x16x32_bf16 v[34:37], v[226:229], v[230:233], v[34:37]
	v_mfma_f32_16x16x32_bf16 v[38:41], v[234:237], v[230:233], v[38:41]
	ds_read_b128 v[202:205], v13 offset:32768
	ds_read_b128 v[210:213], v14 offset:49152
	ds_read_b128 v[214:217], v15 offset:32768
	ds_read_b128 v[218:221], v14 offset:51200
	ds_read_b128 v[222:225], v16 offset:32768
	ds_read_b128 v[226:229], v14 offset:53248
	ds_read_b128 v[230:233], v17 offset:32768
	ds_read_b128 v[234:237], v14 offset:55296
	s_waitcnt vmcnt(0)
	s_waitcnt vmcnt(0) lgkmcnt(0)
	s_barrier
	global_load_lds_dwordx4 v[0:1], off
	s_mov_b32 m0, s19
	v_lshl_add_u64 v[0:1], v[2:3], 0, s[16:17]
	global_load_lds_dwordx4 v[110:111], off
	s_mov_b32 m0, s20
	v_mfma_f32_16x16x32_bf16 v[46:49], v[210:213], v[202:205], v[46:49]
	global_load_lds_dwordx4 v[0:1], off
	s_mov_b32 m0, s21
	v_lshl_add_u64 v[0:1], v[4:5], 0, s[16:17]
	global_load_lds_dwordx4 v[112:113], off
	s_mov_b32 m0, s22
	v_mfma_f32_16x16x32_bf16 v[150:153], v[218:221], v[202:205], v[150:153]
	global_load_lds_dwordx4 v[0:1], off
	s_mov_b32 m0, s23
	v_lshl_add_u64 v[0:1], v[6:7], 0, s[16:17]
	global_load_lds_dwordx4 v[114:115], off
	s_mov_b32 m0, s24
	v_mfma_f32_16x16x32_bf16 v[154:157], v[226:229], v[202:205], v[154:157]
	global_load_lds_dwordx4 v[0:1], off
	s_mov_b32 m0, s25
	v_mfma_f32_16x16x32_bf16 v[42:45], v[234:237], v[202:205], v[42:45]
	global_load_lds_dwordx4 v[116:117], off
	v_mfma_f32_16x16x32_bf16 v[158:161], v[210:213], v[214:217], v[158:161]
	v_mfma_f32_16x16x32_bf16 v[162:165], v[218:221], v[214:217], v[162:165]
	v_mfma_f32_16x16x32_bf16 v[176:179], v[226:229], v[214:217], v[176:179]
	v_mfma_f32_16x16x32_bf16 v[22:25], v[234:237], v[214:217], v[22:25]
	v_mfma_f32_16x16x32_bf16 v[180:183], v[210:213], v[222:225], v[180:183]
	v_mfma_f32_16x16x32_bf16 v[184:187], v[218:221], v[222:225], v[184:187]
	v_mfma_f32_16x16x32_bf16 v[198:201], v[226:229], v[222:225], v[198:201]
	v_mfma_f32_16x16x32_bf16 v[30:33], v[234:237], v[222:225], v[30:33]
	v_mfma_f32_16x16x32_bf16 v[18:21], v[210:213], v[230:233], v[18:21]
	v_mfma_f32_16x16x32_bf16 v[26:29], v[218:221], v[230:233], v[26:29]
	v_mfma_f32_16x16x32_bf16 v[34:37], v[226:229], v[230:233], v[34:37]
	ds_read_b128 v[0:3], v8
	ds_read_b128 v[4:7], v9 offset:16384
	ds_read_b128 v[202:205], v10
	ds_read_b128 v[210:213], v9 offset:18432
	ds_read_b128 v[214:217], v11
	ds_read_b128 v[218:221], v9 offset:20480
	ds_read_b128 v[222:225], v12
	ds_read_b128 v[226:229], v9 offset:22528
	v_mfma_f32_16x16x32_bf16 v[38:41], v[234:237], v[230:233], v[38:41]
	s_waitcnt lgkmcnt(0)
	v_mfma_f32_16x16x32_bf16 v[46:49], v[4:7], v[0:3], v[46:49]
	v_mfma_f32_16x16x32_bf16 v[150:153], v[210:213], v[0:3], v[150:153]
	v_mfma_f32_16x16x32_bf16 v[154:157], v[218:221], v[0:3], v[154:157]
	v_mfma_f32_16x16x32_bf16 v[0:3], v[226:229], v[0:3], v[42:45]
	v_mfma_f32_16x16x32_bf16 v[42:45], v[4:7], v[202:205], v[158:161]
	v_mfma_f32_16x16x32_bf16 v[158:161], v[210:213], v[202:205], v[162:165]
	v_mfma_f32_16x16x32_bf16 v[162:165], v[218:221], v[202:205], v[176:179]
	v_mfma_f32_16x16x32_bf16 v[22:25], v[226:229], v[202:205], v[22:25]
	v_mfma_f32_16x16x32_bf16 v[176:179], v[4:7], v[214:217], v[180:183]
	v_mfma_f32_16x16x32_bf16 v[180:183], v[210:213], v[214:217], v[184:187]
	v_mfma_f32_16x16x32_bf16 v[184:187], v[218:221], v[214:217], v[198:201]
	v_mfma_f32_16x16x32_bf16 v[30:33], v[226:229], v[214:217], v[30:33]
	v_mfma_f32_16x16x32_bf16 v[4:7], v[4:7], v[222:225], v[18:21]
	v_mfma_f32_16x16x32_bf16 v[18:21], v[210:213], v[222:225], v[26:29]
	v_mfma_f32_16x16x32_bf16 v[26:29], v[218:221], v[222:225], v[34:37]
	v_mfma_f32_16x16x32_bf16 v[34:37], v[226:229], v[222:225], v[38:41]
	s_nop 2
	ds_read_b128 v[38:41], v13
	ds_read_b128 v[198:201], v14 offset:16384
	ds_read_b128 v[202:205], v15
	ds_read_b128 v[210:213], v14 offset:18432
	ds_read_b128 v[214:217], v16
	ds_read_b128 v[218:221], v14 offset:20480
	ds_read_b128 v[222:225], v17
	ds_read_b128 v[226:229], v14 offset:22528
	s_waitcnt vmcnt(0)
	s_waitcnt vmcnt(0) lgkmcnt(0)
	v_mfma_f32_16x16x32_bf16 v[46:49], v[198:201], v[38:41], v[46:49]
	s_barrier
; DI unsigned pack2bf(float a, float b) { const f2_t v = {a, b}; return __builtin_bit_cast(unsigned, __builtin_convertvector(v, bf2_t)); }
; template <bool SWAP, class Epi>
; DI void gemm_tile(const u16* __restrict__ Ag, long lda, const u16* __restrict__ Bg, long ldb, int ka0, int ka1, int kb0, int kb1, char* shm, Epi&& epi) {
;     ...
;         Bt[m] = *reinterpret_cast<const bf16x8*>(SB + rb * 128 + (((ks * 4 + fq) ^ ((rb >> 1) & 7)) * 16));
;       }
; #pragma unroll
;       for (int m = 0; m < 4; ++m)
; #pragma unroll
;         for (int n = 0; n < 4; ++n) acc[m][n] = SWAP ? __builtin_amdgcn_mfma_f32_16x16x32_bf16(Bt[n], At[m], acc[m][n], 0, 0, 0) : __builtin_amdgcn_mfma_f32_16x16x32_bf16(At[m], Bt[n], acc[m][n], 0, 0, 0);
; DI void phase5(const Params& P, char* smem) {
;     ...
;     gemm_tile<true>(Yb + (long)brow * 512, 512, WgT + (long)bcol * 512, 512, 0, 8, 0, 0, smem, [&](int row, int col0, f32x4 v) {
;       const long r = brow + row; const int c = bcol + col0;
;       const uint2 yy = *reinterpret_cast<const uint2*>(Yb + r * 512 + c);
;       const float o0 = __uint_as_float(yy.x << 16) / (1.f + __expf(-v[0])), o1 = __uint_as_float(yy.x & 0xffff0000u) / (1.f + __expf(-v[1]));
;       const float o2 = __uint_as_float(yy.y << 16) / (1.f + __expf(-v[2])), o3 = __uint_as_float(yy.y & 0xffff0000u) / (1.f + __expf(-v[3]));
;       *reinterpret_cast<uint2*>(cat + r * 1024 + c) = make_uint2(pack2bf(o0, o1), pack2bf(o2, o3));
	v_mfma_f32_16x16x32_bf16 v[150:153], v[210:213], v[38:41], v[150:153]
	v_mfma_f32_16x16x32_bf16 v[154:157], v[218:221], v[38:41], v[154:157]
	v_mfma_f32_16x16x32_bf16 v[0:3], v[226:229], v[38:41], v[0:3]
	v_mfma_f32_16x16x32_bf16 v[38:41], v[198:201], v[202:205], v[42:45]
	v_mfma_f32_16x16x32_bf16 v[42:45], v[210:213], v[202:205], v[158:161]
	v_mfma_f32_16x16x32_bf16 v[158:161], v[218:221], v[202:205], v[162:165]
	v_mfma_f32_16x16x32_bf16 v[22:25], v[226:229], v[202:205], v[22:25]
	v_mfma_f32_16x16x32_bf16 v[162:165], v[198:201], v[214:217], v[176:179]
	v_mfma_f32_16x16x32_bf16 v[176:179], v[210:213], v[214:217], v[180:183]
	v_mfma_f32_16x16x32_bf16 v[180:183], v[218:221], v[214:217], v[184:187]
	v_mfma_f32_16x16x32_bf16 v[30:33], v[226:229], v[214:217], v[30:33]
	v_mfma_f32_16x16x32_bf16 v[4:7], v[198:201], v[222:225], v[4:7]
	v_mfma_f32_16x16x32_bf16 v[18:21], v[210:213], v[222:225], v[18:21]
	v_mfma_f32_16x16x32_bf16 v[26:29], v[218:221], v[222:225], v[26:29]
	v_mfma_f32_16x16x32_bf16 v[34:37], v[226:229], v[222:225], v[34:37]
	ds_read_b128 v[184:187], v14 offset:55296
	ds_read_b128 v[198:201], v17 offset:32768
	ds_read_b128 v[202:205], v14 offset:53248
	ds_read_b128 v[210:213], v16 offset:32768
	ds_read_b128 v[214:217], v14 offset:51200
	ds_read_b128 v[218:221], v15 offset:32768
	ds_read_b128 v[222:225], v14 offset:49152
	ds_read_b128 v[14:17], v13 offset:32768
	ds_read_b128 v[226:229], v9 offset:55296
	ds_read_b128 v[230:233], v12 offset:32768
	ds_read_b128 v[234:237], v9 offset:53248
	ds_read_b128 v[238:241], v11 offset:32768
	ds_read_b128 v[242:245], v9 offset:51200
	ds_read_b128 v[10:13], v10 offset:32768
	ds_read_b128 v[246:249], v9 offset:49152
	ds_read_b128 v[250:253], v8 offset:32768
	s_waitcnt lgkmcnt(0)
	s_barrier
	v_mfma_f32_16x16x32_bf16 v[46:49], v[246:249], v[250:253], v[46:49]
	v_mfma_f32_16x16x32_bf16 v[38:41], v[246:249], v[10:13], v[38:41]
	v_mfma_f32_16x16x32_bf16 v[158:161], v[234:237], v[10:13], v[158:161]
	v_mfma_f32_16x16x32_bf16 v[150:153], v[242:245], v[250:253], v[150:153]
	v_mfma_f32_16x16x32_bf16 v[154:157], v[234:237], v[250:253], v[154:157]
	v_mfma_f32_16x16x32_bf16 v[0:3], v[226:229], v[250:253], v[0:3]
	v_mfma_f32_16x16x32_bf16 v[250:253], v[242:245], v[10:13], v[42:45]
	v_mfma_f32_16x16x32_bf16 v[8:11], v[226:229], v[10:13], v[22:25]
	v_mfma_f32_16x16x32_bf16 v[22:25], v[246:249], v[238:241], v[162:165]
	v_mfma_f32_16x16x32_bf16 v[162:165], v[242:245], v[238:241], v[176:179]
	v_mfma_f32_16x16x32_bf16 v[176:179], v[234:237], v[238:241], v[180:183]
	v_mfma_f32_16x16x32_bf16 v[180:183], v[226:229], v[238:241], v[30:33]
	v_mfma_f32_16x16x32_bf16 v[4:7], v[246:249], v[230:233], v[4:7]
	v_mfma_f32_16x16x32_bf16 v[238:241], v[242:245], v[230:233], v[18:21]
	v_mfma_f32_16x16x32_bf16 v[234:237], v[234:237], v[230:233], v[26:29]
	v_mfma_f32_16x16x32_bf16 v[226:229], v[226:229], v[230:233], v[34:37]
	v_mfma_f32_16x16x32_bf16 v[230:233], v[222:225], v[14:17], v[46:49]
	v_mfma_f32_16x16x32_bf16 v[44:47], v[222:225], v[218:221], v[38:41]
	v_mfma_f32_16x16x32_bf16 v[36:39], v[202:205], v[218:221], v[158:161]
	s_nop 5
	v_mul_f32_e32 v125, 0xbfb8aa3b, v230
	v_mul_f32_e32 v127, 0xbfb8aa3b, v231
	v_mul_f32_e32 v44, 0xbfb8aa3b, v44
	v_or_b32_e32 v158, v132, v134
	v_ashrrev_i32_e32 v159, 31, v158
	v_lshlrev_b64 v[160:161], 10, v[158:159]
	v_lshl_add_u64 v[160:161], v[118:119], 0, v[160:161]
	v_mfma_f32_16x16x32_bf16 v[28:31], v[222:225], v[210:213], v[22:25]
	v_lshlrev_b64 v[158:159], 11, v[158:159]
	v_lshl_add_u64 v[158:159], v[120:121], 0, v[158:159]
	v_mul_f32_e32 v45, 0xbfb8aa3b, v45
	v_mfma_f32_16x16x32_bf16 v[24:27], v[214:217], v[210:213], v[162:165]
	v_exp_f32_e32 v44, v44
	v_exp_f32_e32 v45, v45
	v_mul_f32_e32 v36, 0xbfb8aa3b, v36
	global_load_dwordx2 v[162:163], v[160:161], off
	v_exp_f32_e32 v164, v125
	v_exp_f32_e32 v165, v127
	v_mfma_f32_16x16x32_bf16 v[150:153], v[214:217], v[14:17], v[150:153]
	v_add_f32_e64 v44, v44, 1.0
	v_add_f32_e64 v45, v45, 1.0
	v_mul_f32_e32 v37, 0xbfb8aa3b, v37
	v_pk_add_f32 v[164:165], v[164:165], 1.0 op_sel_hi:[1,0]
	v_mfma_f32_16x16x32_bf16 v[154:157], v[202:205], v[14:17], v[154:157]
	v_exp_f32_e32 v36, v36
	v_exp_f32_e32 v37, v37
	v_mul_f32_e32 v28, 0xbfb8aa3b, v28
	v_mfma_f32_16x16x32_bf16 v[48:51], v[184:187], v[14:17], v[0:3]
	v_mul_f32_e32 v29, 0xbfb8aa3b, v29
	v_pk_add_f32 v[36:37], v[36:37], 1.0 op_sel_hi:[1,0]
	v_exp_f32_e32 v28, v28
	v_mfma_f32_16x16x32_bf16 v[40:43], v[214:217], v[218:221], v[250:253]
	v_exp_f32_e32 v29, v29
	s_nop 2
	v_mul_f32_e32 v48, 0xbfb8aa3b, v48
	v_mul_f32_e32 v49, 0xbfb8aa3b, v49
	v_exp_f32_e32 v48, v48
	v_exp_f32_e32 v49, v49
	v_mul_f32_e32 v40, 0xbfb8aa3b, v40
	v_mul_f32_e32 v41, 0xbfb8aa3b, v41
	v_exp_f32_e32 v40, v40
	v_pk_add_f32 v[48:49], v[48:49], 1.0 op_sel_hi:[1,0]
	v_exp_f32_e32 v41, v41
	v_mfma_f32_16x16x32_bf16 v[32:35], v[184:187], v[218:221], v[8:11]
	v_add_f32_e64 v28, v28, 1.0
	v_add_f32_e64 v29, v29, 1.0
	v_mul_f32_e32 v24, 0xbfb8aa3b, v24
	v_pk_add_f32 v[40:41], v[40:41], 1.0 op_sel_hi:[1,0]
	v_mul_f32_e32 v25, 0xbfb8aa3b, v25
	v_exp_f32_e32 v24, v24
	s_nop 1
	v_mul_f32_e32 v32, 0xbfb8aa3b, v32
	v_mul_f32_e32 v33, 0xbfb8aa3b, v33
	v_exp_f32_e32 v32, v32
	v_exp_f32_e32 v33, v33
	v_exp_f32_e32 v25, v25
	v_mfma_f32_16x16x32_bf16 v[20:23], v[202:205], v[210:213], v[176:179]
	v_add_f32_e64 v32, v32, 1.0
	v_add_f32_e64 v33, v33, 1.0
	v_pk_add_f32 v[24:25], v[24:25], 1.0 op_sel_hi:[1,0]
	v_mfma_f32_16x16x32_bf16 v[16:19], v[184:187], v[210:213], v[180:183]
	s_waitcnt vmcnt(0)
; DI unsigned pack2bf(float a, float b) { const f2_t v = {a, b}; return __builtin_bit_cast(unsigned, __builtin_convertvector(v, bf2_t)); }
; DI void phase5(const Params& P, char* smem) {
;     ...
;     gemm_tile<true>(Yb + (long)brow * 512, 512, WgT + (long)bcol * 512, 512, 0, 8, 0, 0, smem, [&](int row, int col0, f32x4 v) {
;       const long r = brow + row; const int c = bcol + col0;
;       const uint2 yy = *reinterpret_cast<const uint2*>(Yb + r * 512 + c);
;       const float o0 = __uint_as_float(yy.x << 16) / (1.f + __expf(-v[0])), o1 = __uint_as_float(yy.x & 0xffff0000u) / (1.f + __expf(-v[1]));
;       const float o2 = __uint_as_float(yy.y << 16) / (1.f + __expf(-v[2])), o3 = __uint_as_float(yy.y & 0xffff0000u) / (1.f + __expf(-v[3]));
;       *reinterpret_cast<uint2*>(cat + r * 1024 + c) = make_uint2(pack2bf(o0, o1), pack2bf(o2, o3));
	global_load_dwordx2 v[176:177], v[160:161], off offset:32
	global_load_dwordx2 v[178:179], v[160:161], off offset:64
	global_load_dwordx2 v[180:181], v[160:161], off offset:96
	v_or_b32_e32 v206, v132, v138
	v_ashrrev_i32_e32 v207, 31, v206
	v_lshlrev_b64 v[206:207], 10, v[206:207]
	v_lshl_add_u64 v[206:207], v[118:119], 0, v[206:207]
	global_load_dwordx2 v[182:183], v[206:207], off
	global_load_dwordx2 v[210:211], v[206:207], off offset:32
	global_load_dwordx2 v[212:213], v[206:207], off offset:64
	global_load_dwordx2 v[218:219], v[206:207], off offset:96
	v_or_b32_e32 v206, v132, v140
	v_ashrrev_i32_e32 v207, 31, v206
	v_lshlrev_b64 v[206:207], 10, v[206:207]
	v_lshl_add_u64 v[206:207], v[118:119], 0, v[206:207]
	global_load_dwordx2 v[220:221], v[206:207], off
	global_load_dwordx2 v[230:231], v[206:207], off offset:32
	global_load_dwordx2 v[242:243], v[206:207], off offset:64
	global_load_dwordx2 v[244:245], v[206:207], off offset:96
	v_or_b32_e32 v206, v132, v142
	v_ashrrev_i32_e32 v207, 31, v206
	v_lshlrev_b64 v[206:207], 10, v[206:207]
	v_lshl_add_u64 v[206:207], v[118:119], 0, v[206:207]
	global_load_dwordx2 v[246:247], v[206:207], off
	global_load_dwordx2 v[248:249], v[206:207], off offset:32
	global_load_dwordx2 v[250:251], v[206:207], off offset:64
	global_load_dwordx2 v[252:253], v[206:207], off offset:96
	v_and_b32_e32 v125, 0xffff0000, v162
	v_div_scale_f32 v127, s[20:21], v165, v165, v125
	v_rcp_f32_e32 v131, v127
	v_lshlrev_b32_e32 v123, 16, v162
	v_mul_f32_e32 v20, 0xbfb8aa3b, v20
	v_mul_f32_e32 v21, 0xbfb8aa3b, v21
	v_fma_f32 v133, -v127, v131, 1.0
	v_fmac_f32_e32 v131, v133, v131
	v_div_scale_f32 v133, vcc, v125, v165, v125
	v_mul_f32_e32 v149, v133, v131
	v_fma_f32 v162, -v127, v149, v133
	v_fmac_f32_e32 v149, v162, v131
	v_fma_f32 v127, -v127, v149, v133
	v_div_fmas_f32 v127, v127, v131, v149
	v_div_fixup_f32 v125, v127, v165, v125
	v_div_scale_f32 v127, s[20:21], v164, v164, v123
	v_rcp_f32_e32 v131, v127
	v_exp_f32_e32 v20, v20
	v_exp_f32_e32 v21, v21
	v_mul_f32_e32 v16, 0xbfb8aa3b, v16
	v_fma_f32 v133, -v127, v131, 1.0
	v_fmac_f32_e32 v131, v133, v131
	v_div_scale_f32 v133, vcc, v123, v164, v123
	v_mul_f32_e32 v149, v133, v131
	v_fma_f32 v162, -v127, v149, v133
	v_fmac_f32_e32 v149, v162, v131
	v_fma_f32 v127, -v127, v149, v133
	v_div_fmas_f32 v127, v127, v131, v149
	v_mul_f32_e32 v131, 0xbfb8aa3b, v232
	v_mul_f32_e32 v133, 0xbfb8aa3b, v233
	v_div_fixup_f32 v123, v127, v164, v123
	v_lshlrev_b32_e32 v127, 16, v163
	v_exp_f32_e32 v162, v131
	v_and_b32_e32 v131, 0xffff0000, v163
	v_exp_f32_e32 v163, v133
	v_pk_add_f32 v[20:21], v[20:21], 1.0 op_sel_hi:[1,0]
	v_mul_f32_e32 v17, 0xbfb8aa3b, v17
	v_exp_f32_e32 v16, v16
	v_pk_add_f32 v[162:163], v[162:163], 1.0 op_sel_hi:[1,0]
	v_exp_f32_e32 v17, v17
	v_div_scale_f32 v133, s[20:21], v163, v163, v131
	v_rcp_f32_e32 v149, v133
	v_pk_add_f32 v[16:17], v[16:17], 1.0 op_sel_hi:[1,0]
	v_mfma_f32_16x16x32_bf16 v[12:15], v[222:225], v[198:201], v[4:7]
	v_fma_f32 v164, -v133, v149, 1.0
	v_fmac_f32_e32 v149, v164, v149
	v_div_scale_f32 v164, vcc, v131, v163, v131
	v_mul_f32_e32 v165, v164, v149
	v_fma_f32 v166, -v133, v165, v164
	v_fmac_f32_e32 v165, v166, v149
	v_fma_f32 v133, -v133, v165, v164
	v_div_fmas_f32 v133, v133, v149, v165
	v_div_fixup_f32 v131, v133, v163, v131
	v_div_scale_f32 v133, s[20:21], v162, v162, v127
	v_rcp_f32_e32 v149, v133
	v_mul_f32_e32 v12, 0xbfb8aa3b, v12
	v_mul_f32_e32 v13, 0xbfb8aa3b, v13
	v_exp_f32_e32 v12, v12
	v_fma_f32 v163, -v133, v149, 1.0
	v_fmac_f32_e32 v149, v163, v149
	v_div_scale_f32 v163, vcc, v127, v162, v127
	v_mul_f32_e32 v164, v163, v149
	v_fma_f32 v165, -v133, v164, v163
	v_fmac_f32_e32 v164, v165, v149
	v_fma_f32 v133, -v133, v164, v163
	v_div_fmas_f32 v133, v133, v149, v164
	v_div_fixup_f32 v127, v133, v162, v127
	v_cvt_pk_bf16_f32 v162, v123, v125
	v_cvt_pk_bf16_f32 v163, v127, v131
	global_store_dwordx2 v[158:159], v[162:163], off
	s_waitcnt vmcnt(0)
	v_mov_b32_e32 v162, v176
	v_mov_b32_e32 v163, v177
	v_mul_f32_e32 v125, 0xbfb8aa3b, v150
	v_mul_f32_e32 v127, 0xbfb8aa3b, v151
	v_exp_f32_e32 v150, v125
	v_exp_f32_e32 v151, v127
	v_exp_f32_e32 v13, v13
	v_mfma_f32_16x16x32_bf16 v[8:11], v[214:217], v[198:201], v[238:241]
	v_add_f32_e64 v150, v150, 1.0
	v_add_f32_e64 v151, v151, 1.0
	v_pk_add_f32 v[12:13], v[12:13], 1.0 op_sel_hi:[1,0]
	v_mfma_f32_16x16x32_bf16 v[4:7], v[202:205], v[198:201], v[234:237]
	v_and_b32_e32 v125, 0xffff0000, v162
	v_div_scale_f32 v127, s[20:21], v151, v151, v125
	v_rcp_f32_e32 v131, v127
	v_lshlrev_b32_e32 v123, 16, v162
	v_mul_f32_e32 v8, 0xbfb8aa3b, v8
	v_mul_f32_e32 v9, 0xbfb8aa3b, v9
	v_fma_f32 v133, -v127, v131, 1.0
	v_fmac_f32_e32 v131, v133, v131
	v_div_scale_f32 v133, vcc, v125, v151, v125
	v_mul_f32_e32 v149, v133, v131
	v_fma_f32 v162, -v127, v149, v133
	v_fmac_f32_e32 v149, v162, v131
	v_fma_f32 v127, -v127, v149, v133
	v_div_fmas_f32 v127, v127, v131, v149
	v_div_fixup_f32 v125, v127, v151, v125
	v_div_scale_f32 v127, s[20:21], v150, v150, v123
	v_rcp_f32_e32 v131, v127
	v_exp_f32_e32 v8, v8
	v_exp_f32_e32 v9, v9
	v_mul_f32_e32 v4, 0xbfb8aa3b, v4
	v_fma_f32 v133, -v127, v131, 1.0
	v_fmac_f32_e32 v131, v133, v131
	v_div_scale_f32 v133, vcc, v123, v150, v123
	v_mul_f32_e32 v149, v133, v131
	v_fma_f32 v151, -v127, v149, v133
	v_fmac_f32_e32 v149, v151, v131
	v_fma_f32 v127, -v127, v149, v133
	v_div_fmas_f32 v127, v127, v131, v149
	v_mul_f32_e32 v131, 0xbfb8aa3b, v152
	v_mul_f32_e32 v133, 0xbfb8aa3b, v153
	v_div_fixup_f32 v123, v127, v150, v123
	v_exp_f32_e32 v150, v131
	v_exp_f32_e32 v151, v133
	v_and_b32_e32 v131, 0xffff0000, v163
	v_lshlrev_b32_e32 v127, 16, v163
	v_pk_add_f32 v[8:9], v[8:9], 1.0 op_sel_hi:[1,0]
; DI unsigned pack2bf(float a, float b) { const f2_t v = {a, b}; return __builtin_bit_cast(unsigned, __builtin_convertvector(v, bf2_t)); }
; DI void phase5(const Params& P, char* smem) {
;     ...
;     gemm_tile<true>(Yb + (long)brow * 512, 512, WgT + (long)bcol * 512, 512, 0, 8, 0, 0, smem, [&](int row, int col0, f32x4 v) {
;       const long r = brow + row; const int c = bcol + col0;
;       const uint2 yy = *reinterpret_cast<const uint2*>(Yb + r * 512 + c);
;       const float o0 = __uint_as_float(yy.x << 16) / (1.f + __expf(-v[0])), o1 = __uint_as_float(yy.x & 0xffff0000u) / (1.f + __expf(-v[1]));
;       const float o2 = __uint_as_float(yy.y << 16) / (1.f + __expf(-v[2])), o3 = __uint_as_float(yy.y & 0xffff0000u) / (1.f + __expf(-v[3]));
;       *reinterpret_cast<uint2*>(cat + r * 1024 + c) = make_uint2(pack2bf(o0, o1), pack2bf(o2, o3));
	v_pk_add_f32 v[150:151], v[150:151], 1.0 op_sel_hi:[1,0]
	v_mul_f32_e32 v5, 0xbfb8aa3b, v5
	v_div_scale_f32 v133, s[20:21], v151, v151, v131
	v_rcp_f32_e32 v149, v133
	v_exp_f32_e32 v4, v4
	v_exp_f32_e32 v5, v5
	v_mfma_f32_16x16x32_bf16 v[0:3], v[184:187], v[198:201], v[226:229]
	v_fma_f32 v152, -v133, v149, 1.0
	v_fmac_f32_e32 v149, v152, v149
	v_div_scale_f32 v152, vcc, v131, v151, v131
	v_mul_f32_e32 v153, v152, v149
	v_fma_f32 v162, -v133, v153, v152
	v_fmac_f32_e32 v153, v162, v149
	v_fma_f32 v133, -v133, v153, v152
	v_div_fmas_f32 v133, v133, v149, v153
	v_div_fixup_f32 v131, v133, v151, v131
	v_div_scale_f32 v133, s[20:21], v150, v150, v127
	v_rcp_f32_e32 v149, v133
	v_pk_add_f32 v[4:5], v[4:5], 1.0 op_sel_hi:[1,0]
	v_mul_f32_e32 v0, 0xbfb8aa3b, v0
	v_mul_f32_e32 v1, 0xbfb8aa3b, v1
	v_fma_f32 v151, -v133, v149, 1.0
	v_fmac_f32_e32 v149, v151, v149
	v_div_scale_f32 v151, vcc, v127, v150, v127
	v_mul_f32_e32 v152, v151, v149
	v_fma_f32 v153, -v133, v152, v151
	v_fmac_f32_e32 v152, v153, v149
	v_fma_f32 v133, -v133, v152, v151
	v_div_fmas_f32 v133, v133, v149, v152
	v_div_fixup_f32 v127, v133, v150, v127
	v_cvt_pk_bf16_f32 v150, v123, v125
	v_cvt_pk_bf16_f32 v151, v127, v131
	global_store_dwordx2 v[158:159], v[150:151], off offset:32
	v_mov_b32_e32 v150, v178
	v_mov_b32_e32 v151, v179
	v_mul_f32_e32 v125, 0xbfb8aa3b, v154
	v_mul_f32_e32 v127, 0xbfb8aa3b, v155
	v_exp_f32_e32 v152, v125
	v_exp_f32_e32 v153, v127
	v_exp_f32_e32 v0, v0
	v_exp_f32_e32 v1, v1
	v_pk_add_f32 v[152:153], v[152:153], 1.0 op_sel_hi:[1,0]
	v_pk_add_f32 v[0:1], v[0:1], 1.0 op_sel_hi:[1,0]
	v_and_b32_e32 v125, 0xffff0000, v150
	v_div_scale_f32 v127, s[20:21], v153, v153, v125
	v_rcp_f32_e32 v131, v127
	v_lshlrev_b32_e32 v123, 16, v150
	v_fma_f32 v133, -v127, v131, 1.0
	v_fmac_f32_e32 v131, v133, v131
	v_div_scale_f32 v133, vcc, v125, v153, v125
	v_mul_f32_e32 v149, v133, v131
	v_fma_f32 v150, -v127, v149, v133
	v_fmac_f32_e32 v149, v150, v131
	v_fma_f32 v127, -v127, v149, v133
	v_div_fmas_f32 v127, v127, v131, v149
	v_div_fixup_f32 v125, v127, v153, v125
	v_div_scale_f32 v127, s[20:21], v152, v152, v123
	v_rcp_f32_e32 v131, v127
	s_nop 0
	v_fma_f32 v133, -v127, v131, 1.0
	v_fmac_f32_e32 v131, v133, v131
	v_div_scale_f32 v133, vcc, v123, v152, v123
	v_mul_f32_e32 v149, v133, v131
	v_fma_f32 v150, -v127, v149, v133
	v_fmac_f32_e32 v149, v150, v131
	v_fma_f32 v127, -v127, v149, v133
	v_div_fmas_f32 v127, v127, v131, v149
	v_mul_f32_e32 v131, 0xbfb8aa3b, v156
	v_mul_f32_e32 v133, 0xbfb8aa3b, v157
	v_div_fixup_f32 v123, v127, v152, v123
	v_lshlrev_b32_e32 v127, 16, v151
	v_exp_f32_e32 v150, v131
	v_and_b32_e32 v131, 0xffff0000, v151
	v_exp_f32_e32 v151, v133
	s_nop 0
	v_pk_add_f32 v[150:151], v[150:151], 1.0 op_sel_hi:[1,0]
	s_nop 0
	v_div_scale_f32 v133, s[20:21], v151, v151, v131
	v_rcp_f32_e32 v149, v133
	s_nop 0
	v_fma_f32 v152, -v133, v149, 1.0
	v_fmac_f32_e32 v149, v152, v149
	v_div_scale_f32 v152, vcc, v131, v151, v131
	v_mul_f32_e32 v153, v152, v149
	v_fma_f32 v154, -v133, v153, v152
	v_fmac_f32_e32 v153, v154, v149
	v_fma_f32 v133, -v133, v153, v152
	v_div_fmas_f32 v133, v133, v149, v153
	v_div_fixup_f32 v131, v133, v151, v131
	v_div_scale_f32 v133, s[20:21], v150, v150, v127
	v_rcp_f32_e32 v149, v133
	s_nop 0
	v_fma_f32 v151, -v133, v149, 1.0
	v_fmac_f32_e32 v149, v151, v149
	v_div_scale_f32 v151, vcc, v127, v150, v127
	v_mul_f32_e32 v152, v151, v149
	v_fma_f32 v153, -v133, v152, v151
	v_fmac_f32_e32 v152, v153, v149
	v_fma_f32 v133, -v133, v152, v151
	v_div_fmas_f32 v133, v133, v149, v152
	v_div_fixup_f32 v127, v133, v150, v127
	v_cvt_pk_bf16_f32 v150, v123, v125
	v_cvt_pk_bf16_f32 v151, v127, v131
	global_store_dwordx2 v[158:159], v[150:151], off offset:64
	v_mov_b32_e32 v150, v180
	v_mov_b32_e32 v151, v181
	v_and_b32_e32 v125, 0xffff0000, v150
	v_div_scale_f32 v127, s[20:21], v49, v49, v125
	v_rcp_f32_e32 v131, v127
	v_lshlrev_b32_e32 v123, 16, v150
	v_fma_f32 v133, -v127, v131, 1.0
	v_fmac_f32_e32 v131, v133, v131
	v_div_scale_f32 v133, vcc, v125, v49, v125
	v_mul_f32_e32 v149, v133, v131
	v_fma_f32 v150, -v127, v149, v133
	v_fmac_f32_e32 v149, v150, v131
	v_fma_f32 v127, -v127, v149, v133
	v_div_fmas_f32 v127, v127, v131, v149
	v_div_fixup_f32 v125, v127, v49, v125
	v_div_scale_f32 v49, s[20:21], v48, v48, v123
	v_rcp_f32_e32 v127, v49
	s_nop 0
	v_fma_f32 v131, -v49, v127, 1.0
	v_fmac_f32_e32 v127, v131, v127
	v_div_scale_f32 v131, vcc, v123, v48, v123
	v_mul_f32_e32 v133, v131, v127
	v_fma_f32 v149, -v49, v133, v131
	v_fmac_f32_e32 v133, v149, v127
	v_fma_f32 v49, -v49, v133, v131
	v_div_fmas_f32 v49, v49, v127, v133
	v_div_fixup_f32 v123, v49, v48, v123
	v_mul_f32_e32 v48, 0xbfb8aa3b, v50
	v_mul_f32_e32 v49, 0xbfb8aa3b, v51
	v_exp_f32_e32 v48, v48
	v_exp_f32_e32 v49, v49
	v_and_b32_e32 v50, 0xffff0000, v151
	v_lshlrev_b32_e32 v127, 16, v151
	v_pk_add_f32 v[48:49], v[48:49], 1.0 op_sel_hi:[1,0]
	s_nop 0
	v_div_scale_f32 v51, s[20:21], v49, v49, v50
	v_rcp_f32_e32 v131, v51
	s_nop 0
	v_fma_f32 v133, -v51, v131, 1.0
	v_fmac_f32_e32 v131, v133, v131
	v_div_scale_f32 v133, vcc, v50, v49, v50
	v_mul_f32_e32 v149, v133, v131
	v_fma_f32 v150, -v51, v149, v133
	v_fmac_f32_e32 v149, v150, v131
	v_fma_f32 v51, -v51, v149, v133
	v_div_fmas_f32 v51, v51, v131, v149
	v_div_fixup_f32 v49, v51, v49, v50
	v_div_scale_f32 v50, s[20:21], v48, v48, v127
	v_rcp_f32_e32 v51, v50
	s_nop 0
	v_fma_f32 v131, -v50, v51, 1.0
	v_fmac_f32_e32 v51, v131, v51
	v_div_scale_f32 v131, vcc, v127, v48, v127
	v_mul_f32_e32 v133, v131, v51
	v_fma_f32 v149, -v50, v133, v131
	v_fmac_f32_e32 v133, v149, v51
	v_fma_f32 v50, -v50, v133, v131
	v_div_fmas_f32 v50, v50, v51, v133
; DI unsigned pack2bf(float a, float b) { const f2_t v = {a, b}; return __builtin_bit_cast(unsigned, __builtin_convertvector(v, bf2_t)); }
; DI void phase5(const Params& P, char* smem) {
;     ...
;     gemm_tile<true>(Yb + (long)brow * 512, 512, WgT + (long)bcol * 512, 512, 0, 8, 0, 0, smem, [&](int row, int col0, f32x4 v) {
;       const long r = brow + row; const int c = bcol + col0;
;       const uint2 yy = *reinterpret_cast<const uint2*>(Yb + r * 512 + c);
;       const float o0 = __uint_as_float(yy.x << 16) / (1.f + __expf(-v[0])), o1 = __uint_as_float(yy.x & 0xffff0000u) / (1.f + __expf(-v[1]));
;       const float o2 = __uint_as_float(yy.y << 16) / (1.f + __expf(-v[2])), o3 = __uint_as_float(yy.y & 0xffff0000u) / (1.f + __expf(-v[3]));
;       *reinterpret_cast<uint2*>(cat + r * 1024 + c) = make_uint2(pack2bf(o0, o1), pack2bf(o2, o3));
	v_div_fixup_f32 v50, v50, v48, v127
	v_cvt_pk_bf16_f32 v48, v123, v125
	v_cvt_pk_bf16_f32 v49, v50, v49
	global_store_dwordx2 v[158:159], v[48:49], off offset:96
	v_or_b32_e32 v48, v132, v138
	v_ashrrev_i32_e32 v49, 31, v48
	v_lshlrev_b64 v[50:51], 10, v[48:49]
	v_lshl_add_u64 v[50:51], v[118:119], 0, v[50:51]
	v_mov_b32_e32 v150, v182
	v_mov_b32_e32 v151, v183
	v_and_b32_e32 v125, 0xffff0000, v150
	v_div_scale_f32 v127, s[20:21], v45, v45, v125
	v_rcp_f32_e32 v131, v127
	v_lshlrev_b32_e32 v123, 16, v150
	v_fma_f32 v133, -v127, v131, 1.0
	v_fmac_f32_e32 v131, v133, v131
	v_div_scale_f32 v133, vcc, v125, v45, v125
	v_mul_f32_e32 v149, v133, v131
	v_fma_f32 v150, -v127, v149, v133
	v_fmac_f32_e32 v149, v150, v131
	v_fma_f32 v127, -v127, v149, v133
	v_div_fmas_f32 v127, v127, v131, v149
	v_div_fixup_f32 v125, v127, v45, v125
	v_div_scale_f32 v45, s[20:21], v44, v44, v123
	v_rcp_f32_e32 v127, v45
	s_nop 0
	v_fma_f32 v131, -v45, v127, 1.0
	v_fmac_f32_e32 v127, v131, v127
	v_div_scale_f32 v131, vcc, v123, v44, v123
	v_mul_f32_e32 v133, v131, v127
	v_fma_f32 v149, -v45, v133, v131
	v_fmac_f32_e32 v133, v149, v127
	v_fma_f32 v45, -v45, v133, v131
	v_div_fmas_f32 v45, v45, v127, v133
	v_div_fixup_f32 v123, v45, v44, v123
	v_mul_f32_e32 v44, 0xbfb8aa3b, v46
	v_mul_f32_e32 v45, 0xbfb8aa3b, v47
	v_exp_f32_e32 v44, v44
	v_exp_f32_e32 v45, v45
	v_and_b32_e32 v46, 0xffff0000, v151
	v_lshlrev_b32_e32 v127, 16, v151
	v_pk_add_f32 v[44:45], v[44:45], 1.0 op_sel_hi:[1,0]
	s_nop 0
	v_div_scale_f32 v47, s[20:21], v45, v45, v46
	v_rcp_f32_e32 v131, v47
	s_nop 0
	v_fma_f32 v133, -v47, v131, 1.0
	v_fmac_f32_e32 v131, v133, v131
	v_div_scale_f32 v133, vcc, v46, v45, v46
	v_mul_f32_e32 v149, v133, v131
	v_fma_f32 v150, -v47, v149, v133
	v_fmac_f32_e32 v149, v150, v131
	v_fma_f32 v47, -v47, v149, v133
	v_div_fmas_f32 v47, v47, v131, v149
	v_div_fixup_f32 v45, v47, v45, v46
	v_div_scale_f32 v46, s[20:21], v44, v44, v127
	v_rcp_f32_e32 v47, v46
	s_nop 0
	v_fma_f32 v131, -v46, v47, 1.0
	v_fmac_f32_e32 v47, v131, v47
	v_div_scale_f32 v131, vcc, v127, v44, v127
	v_mul_f32_e32 v133, v131, v47
	v_fma_f32 v149, -v46, v133, v131
	v_fmac_f32_e32 v133, v149, v47
	v_fma_f32 v46, -v46, v133, v131
	v_div_fmas_f32 v46, v46, v47, v133
	v_div_fixup_f32 v46, v46, v44, v127
	v_cvt_pk_bf16_f32 v45, v46, v45
	v_lshlrev_b64 v[46:47], 11, v[48:49]
	v_cvt_pk_bf16_f32 v44, v123, v125
	v_lshl_add_u64 v[46:47], v[120:121], 0, v[46:47]
	global_store_dwordx2 v[46:47], v[44:45], off
	v_mov_b32_e32 v44, v210
	v_mov_b32_e32 v45, v211
	v_lshlrev_b32_e32 v48, 16, v44
	v_and_b32_e32 v44, 0xffff0000, v44
	v_div_scale_f32 v49, s[20:21], v41, v41, v44
	v_rcp_f32_e32 v123, v49
	s_nop 0
	v_fma_f32 v125, -v49, v123, 1.0
	v_fmac_f32_e32 v123, v125, v123
	v_div_scale_f32 v125, vcc, v44, v41, v44
	v_mul_f32_e32 v127, v125, v123
	v_fma_f32 v131, -v49, v127, v125
	v_fmac_f32_e32 v127, v131, v123
	v_fma_f32 v49, -v49, v127, v125
	v_div_fmas_f32 v49, v49, v123, v127
	v_div_fixup_f32 v44, v49, v41, v44
	v_div_scale_f32 v41, s[20:21], v40, v40, v48
	v_rcp_f32_e32 v49, v41
	s_nop 0
	v_fma_f32 v123, -v41, v49, 1.0
	v_fmac_f32_e32 v49, v123, v49
	v_div_scale_f32 v123, vcc, v48, v40, v48
	v_mul_f32_e32 v125, v123, v49
	v_fma_f32 v127, -v41, v125, v123
	v_fmac_f32_e32 v125, v127, v49
	v_fma_f32 v41, -v41, v125, v123
	v_div_fmas_f32 v41, v41, v49, v125
	v_div_fixup_f32 v48, v41, v40, v48
	v_mul_f32_e32 v40, 0xbfb8aa3b, v42
	v_mul_f32_e32 v41, 0xbfb8aa3b, v43
	v_exp_f32_e32 v40, v40
	v_exp_f32_e32 v41, v41
	v_and_b32_e32 v42, 0xffff0000, v45
	v_lshlrev_b32_e32 v49, 16, v45
	v_pk_add_f32 v[40:41], v[40:41], 1.0 op_sel_hi:[1,0]
	s_nop 0
	v_div_scale_f32 v43, s[20:21], v41, v41, v42
	v_rcp_f32_e32 v45, v43
	s_nop 0
	v_fma_f32 v123, -v43, v45, 1.0
	v_fmac_f32_e32 v45, v123, v45
	v_div_scale_f32 v123, vcc, v42, v41, v42
	v_mul_f32_e32 v125, v123, v45
	v_fma_f32 v127, -v43, v125, v123
	v_fmac_f32_e32 v125, v127, v45
	v_fma_f32 v43, -v43, v125, v123
	v_div_fmas_f32 v43, v43, v45, v125
	v_div_fixup_f32 v41, v43, v41, v42
	v_div_scale_f32 v42, s[20:21], v40, v40, v49
	v_rcp_f32_e32 v43, v42
	s_nop 0
	v_fma_f32 v45, -v42, v43, 1.0
	v_fmac_f32_e32 v43, v45, v43
	v_div_scale_f32 v45, vcc, v49, v40, v49
	v_mul_f32_e32 v123, v45, v43
	v_fma_f32 v125, -v42, v123, v45
	v_fmac_f32_e32 v123, v125, v43
	v_fma_f32 v42, -v42, v123, v45
	v_div_fmas_f32 v42, v42, v43, v123
	v_div_fixup_f32 v42, v42, v40, v49
	v_cvt_pk_bf16_f32 v40, v48, v44
	v_cvt_pk_bf16_f32 v41, v42, v41
	global_store_dwordx2 v[46:47], v[40:41], off offset:32
	v_mov_b32_e32 v40, v212
	v_mov_b32_e32 v41, v213
	v_lshlrev_b32_e32 v42, 16, v40
	v_and_b32_e32 v40, 0xffff0000, v40
	v_div_scale_f32 v43, s[20:21], v37, v37, v40
	v_rcp_f32_e32 v44, v43
	s_nop 0
	v_fma_f32 v45, -v43, v44, 1.0
	v_fmac_f32_e32 v44, v45, v44
	v_div_scale_f32 v45, vcc, v40, v37, v40
	v_mul_f32_e32 v48, v45, v44
	v_fma_f32 v49, -v43, v48, v45
	v_fmac_f32_e32 v48, v49, v44
	v_fma_f32 v43, -v43, v48, v45
	v_div_fmas_f32 v43, v43, v44, v48
	v_div_fixup_f32 v40, v43, v37, v40
	v_div_scale_f32 v37, s[20:21], v36, v36, v42
	v_rcp_f32_e32 v43, v37
	s_nop 0
	v_fma_f32 v44, -v37, v43, 1.0
	v_fmac_f32_e32 v43, v44, v43
	v_div_scale_f32 v44, vcc, v42, v36, v42
	v_mul_f32_e32 v45, v44, v43
	v_fma_f32 v48, -v37, v45, v44
	v_fmac_f32_e32 v45, v48, v43
	v_fma_f32 v37, -v37, v45, v44
	v_div_fmas_f32 v37, v37, v43, v45
	v_div_fixup_f32 v42, v37, v36, v42
	v_mul_f32_e32 v36, 0xbfb8aa3b, v38
	v_mul_f32_e32 v37, 0xbfb8aa3b, v39
	v_exp_f32_e32 v36, v36
	v_exp_f32_e32 v37, v37
	v_and_b32_e32 v38, 0xffff0000, v41
	v_lshlrev_b32_e32 v43, 16, v41
	v_pk_add_f32 v[36:37], v[36:37], 1.0 op_sel_hi:[1,0]
	s_nop 0
; DI unsigned pack2bf(float a, float b) { const f2_t v = {a, b}; return __builtin_bit_cast(unsigned, __builtin_convertvector(v, bf2_t)); }
; DI void phase5(const Params& P, char* smem) {
;     ...
;     gemm_tile<true>(Yb + (long)brow * 512, 512, WgT + (long)bcol * 512, 512, 0, 8, 0, 0, smem, [&](int row, int col0, f32x4 v) {
;       const long r = brow + row; const int c = bcol + col0;
;       const uint2 yy = *reinterpret_cast<const uint2*>(Yb + r * 512 + c);
;       const float o0 = __uint_as_float(yy.x << 16) / (1.f + __expf(-v[0])), o1 = __uint_as_float(yy.x & 0xffff0000u) / (1.f + __expf(-v[1]));
;       const float o2 = __uint_as_float(yy.y << 16) / (1.f + __expf(-v[2])), o3 = __uint_as_float(yy.y & 0xffff0000u) / (1.f + __expf(-v[3]));
;       *reinterpret_cast<uint2*>(cat + r * 1024 + c) = make_uint2(pack2bf(o0, o1), pack2bf(o2, o3));
	v_div_scale_f32 v39, s[20:21], v37, v37, v38
	v_rcp_f32_e32 v41, v39
	s_nop 0
	v_fma_f32 v44, -v39, v41, 1.0
	v_fmac_f32_e32 v41, v44, v41
	v_div_scale_f32 v44, vcc, v38, v37, v38
	v_mul_f32_e32 v45, v44, v41
	v_fma_f32 v48, -v39, v45, v44
	v_fmac_f32_e32 v45, v48, v41
	v_fma_f32 v39, -v39, v45, v44
	v_div_fmas_f32 v39, v39, v41, v45
	v_div_fixup_f32 v37, v39, v37, v38
	v_div_scale_f32 v38, s[20:21], v36, v36, v43
	v_rcp_f32_e32 v39, v38
	s_nop 0
	v_fma_f32 v41, -v38, v39, 1.0
	v_fmac_f32_e32 v39, v41, v39
	v_div_scale_f32 v41, vcc, v43, v36, v43
	v_mul_f32_e32 v44, v41, v39
	v_fma_f32 v45, -v38, v44, v41
	v_fmac_f32_e32 v44, v45, v39
	v_fma_f32 v38, -v38, v44, v41
	v_div_fmas_f32 v38, v38, v39, v44
	v_div_fixup_f32 v38, v38, v36, v43
	v_cvt_pk_bf16_f32 v36, v42, v40
	v_cvt_pk_bf16_f32 v37, v38, v37
	global_store_dwordx2 v[46:47], v[36:37], off offset:64
	v_mov_b32_e32 v36, v218
	v_mov_b32_e32 v37, v219
	v_lshlrev_b32_e32 v38, 16, v36
	v_and_b32_e32 v36, 0xffff0000, v36
	v_div_scale_f32 v39, s[20:21], v33, v33, v36
	v_rcp_f32_e32 v40, v39
	s_nop 0
	v_fma_f32 v41, -v39, v40, 1.0
	v_fmac_f32_e32 v40, v41, v40
	v_div_scale_f32 v41, vcc, v36, v33, v36
	v_mul_f32_e32 v42, v41, v40
	v_fma_f32 v43, -v39, v42, v41
	v_fmac_f32_e32 v42, v43, v40
	v_fma_f32 v39, -v39, v42, v41
	v_div_fmas_f32 v39, v39, v40, v42
	v_div_fixup_f32 v36, v39, v33, v36
	v_div_scale_f32 v33, s[20:21], v32, v32, v38
	v_rcp_f32_e32 v39, v33
	s_nop 0
	v_fma_f32 v40, -v33, v39, 1.0
	v_fmac_f32_e32 v39, v40, v39
	v_div_scale_f32 v40, vcc, v38, v32, v38
	v_mul_f32_e32 v41, v40, v39
	v_fma_f32 v42, -v33, v41, v40
	v_fmac_f32_e32 v41, v42, v39
	v_fma_f32 v33, -v33, v41, v40
	v_div_fmas_f32 v33, v33, v39, v41
	v_div_fixup_f32 v38, v33, v32, v38
	v_mul_f32_e32 v32, 0xbfb8aa3b, v34
	v_mul_f32_e32 v33, 0xbfb8aa3b, v35
	v_exp_f32_e32 v32, v32
	v_exp_f32_e32 v33, v33
	v_and_b32_e32 v34, 0xffff0000, v37
	v_lshlrev_b32_e32 v39, 16, v37
	v_pk_add_f32 v[32:33], v[32:33], 1.0 op_sel_hi:[1,0]
	s_nop 0
	v_div_scale_f32 v35, s[20:21], v33, v33, v34
	v_rcp_f32_e32 v37, v35
	s_nop 0
	v_fma_f32 v40, -v35, v37, 1.0
	v_fmac_f32_e32 v37, v40, v37
	v_div_scale_f32 v40, vcc, v34, v33, v34
	v_mul_f32_e32 v41, v40, v37
	v_fma_f32 v42, -v35, v41, v40
	v_fmac_f32_e32 v41, v42, v37
	v_fma_f32 v35, -v35, v41, v40
	v_div_fmas_f32 v35, v35, v37, v41
	v_div_fixup_f32 v33, v35, v33, v34
	v_div_scale_f32 v34, s[20:21], v32, v32, v39
	v_rcp_f32_e32 v35, v34
	s_nop 0
	v_fma_f32 v37, -v34, v35, 1.0
	v_fmac_f32_e32 v35, v37, v35
	v_div_scale_f32 v37, vcc, v39, v32, v39
	v_mul_f32_e32 v40, v37, v35
	v_fma_f32 v41, -v34, v40, v37
	v_fmac_f32_e32 v40, v41, v35
	v_fma_f32 v34, -v34, v40, v37
	v_div_fmas_f32 v34, v34, v35, v40
	v_div_fixup_f32 v34, v34, v32, v39
	v_cvt_pk_bf16_f32 v32, v38, v36
	v_cvt_pk_bf16_f32 v33, v34, v33
	global_store_dwordx2 v[46:47], v[32:33], off offset:96
	v_or_b32_e32 v32, v132, v140
	v_ashrrev_i32_e32 v33, 31, v32
	v_lshlrev_b64 v[34:35], 10, v[32:33]
	v_lshl_add_u64 v[34:35], v[118:119], 0, v[34:35]
	v_mov_b32_e32 v36, v220
	v_mov_b32_e32 v37, v221
	v_lshlrev_b32_e32 v38, 16, v36
	v_and_b32_e32 v36, 0xffff0000, v36
	v_div_scale_f32 v39, s[20:21], v29, v29, v36
	v_rcp_f32_e32 v40, v39
	s_nop 0
	v_fma_f32 v41, -v39, v40, 1.0
	v_fmac_f32_e32 v40, v41, v40
	v_div_scale_f32 v41, vcc, v36, v29, v36
	v_mul_f32_e32 v42, v41, v40
	v_fma_f32 v43, -v39, v42, v41
	v_fmac_f32_e32 v42, v43, v40
	v_fma_f32 v39, -v39, v42, v41
	v_div_fmas_f32 v39, v39, v40, v42
	v_div_fixup_f32 v36, v39, v29, v36
	v_div_scale_f32 v29, s[20:21], v28, v28, v38
	v_rcp_f32_e32 v39, v29
	s_nop 0
	v_fma_f32 v40, -v29, v39, 1.0
	v_fmac_f32_e32 v39, v40, v39
	v_div_scale_f32 v40, vcc, v38, v28, v38
	v_mul_f32_e32 v41, v40, v39
	v_fma_f32 v42, -v29, v41, v40
	v_fmac_f32_e32 v41, v42, v39
	v_fma_f32 v29, -v29, v41, v40
	v_div_fmas_f32 v29, v29, v39, v41
	v_div_fixup_f32 v38, v29, v28, v38
	v_mul_f32_e32 v28, 0xbfb8aa3b, v30
	v_mul_f32_e32 v29, 0xbfb8aa3b, v31
	v_exp_f32_e32 v28, v28
	v_exp_f32_e32 v29, v29
	v_and_b32_e32 v30, 0xffff0000, v37
	v_lshlrev_b32_e32 v39, 16, v37
	v_pk_add_f32 v[28:29], v[28:29], 1.0 op_sel_hi:[1,0]
	s_nop 0
	v_div_scale_f32 v31, s[20:21], v29, v29, v30
	v_rcp_f32_e32 v37, v31
	s_nop 0
	v_fma_f32 v40, -v31, v37, 1.0
	v_fmac_f32_e32 v37, v40, v37
	v_div_scale_f32 v40, vcc, v30, v29, v30
	v_mul_f32_e32 v41, v40, v37
	v_fma_f32 v42, -v31, v41, v40
	v_fmac_f32_e32 v41, v42, v37
	v_fma_f32 v31, -v31, v41, v40
	v_div_fmas_f32 v31, v31, v37, v41
	v_div_fixup_f32 v29, v31, v29, v30
	v_div_scale_f32 v30, s[20:21], v28, v28, v39
	v_rcp_f32_e32 v31, v30
	s_nop 0
	v_fma_f32 v37, -v30, v31, 1.0
	v_fmac_f32_e32 v31, v37, v31
	v_div_scale_f32 v37, vcc, v39, v28, v39
	v_mul_f32_e32 v40, v37, v31
	v_fma_f32 v41, -v30, v40, v37
	v_fmac_f32_e32 v40, v41, v31
	v_fma_f32 v30, -v30, v40, v37
	v_div_fmas_f32 v30, v30, v31, v40
	v_div_fixup_f32 v30, v30, v28, v39
	v_cvt_pk_bf16_f32 v29, v30, v29
	v_lshlrev_b64 v[30:31], 11, v[32:33]
	v_cvt_pk_bf16_f32 v28, v38, v36
	v_lshl_add_u64 v[30:31], v[120:121], 0, v[30:31]
	global_store_dwordx2 v[30:31], v[28:29], off
	v_mov_b32_e32 v28, v230
	v_mov_b32_e32 v29, v231
	v_lshlrev_b32_e32 v32, 16, v28
	v_and_b32_e32 v28, 0xffff0000, v28
	v_div_scale_f32 v33, s[20:21], v25, v25, v28
	v_rcp_f32_e32 v36, v33
	s_nop 0
	v_fma_f32 v37, -v33, v36, 1.0
	v_fmac_f32_e32 v36, v37, v36
	v_div_scale_f32 v37, vcc, v28, v25, v28
	v_mul_f32_e32 v38, v37, v36
	v_fma_f32 v39, -v33, v38, v37
	v_fmac_f32_e32 v38, v39, v36
	v_fma_f32 v33, -v33, v38, v37
	v_div_fmas_f32 v33, v33, v36, v38
	v_div_fixup_f32 v28, v33, v25, v28
	v_div_scale_f32 v25, s[20:21], v24, v24, v32
	v_rcp_f32_e32 v33, v25
	s_nop 0
; DI unsigned pack2bf(float a, float b) { const f2_t v = {a, b}; return __builtin_bit_cast(unsigned, __builtin_convertvector(v, bf2_t)); }
; DI void phase5(const Params& P, char* smem) {
;     ...
;     gemm_tile<true>(Yb + (long)brow * 512, 512, WgT + (long)bcol * 512, 512, 0, 8, 0, 0, smem, [&](int row, int col0, f32x4 v) {
;       const long r = brow + row; const int c = bcol + col0;
;       const uint2 yy = *reinterpret_cast<const uint2*>(Yb + r * 512 + c);
;       const float o0 = __uint_as_float(yy.x << 16) / (1.f + __expf(-v[0])), o1 = __uint_as_float(yy.x & 0xffff0000u) / (1.f + __expf(-v[1]));
;       const float o2 = __uint_as_float(yy.y << 16) / (1.f + __expf(-v[2])), o3 = __uint_as_float(yy.y & 0xffff0000u) / (1.f + __expf(-v[3]));
;       *reinterpret_cast<uint2*>(cat + r * 1024 + c) = make_uint2(pack2bf(o0, o1), pack2bf(o2, o3));
	v_fma_f32 v36, -v25, v33, 1.0
	v_fmac_f32_e32 v33, v36, v33
	v_div_scale_f32 v36, vcc, v32, v24, v32
	v_mul_f32_e32 v37, v36, v33
	v_fma_f32 v38, -v25, v37, v36
	v_fmac_f32_e32 v37, v38, v33
	v_fma_f32 v25, -v25, v37, v36
	v_div_fmas_f32 v25, v25, v33, v37
	v_div_fixup_f32 v32, v25, v24, v32
	v_mul_f32_e32 v24, 0xbfb8aa3b, v26
	v_mul_f32_e32 v25, 0xbfb8aa3b, v27
	v_exp_f32_e32 v24, v24
	v_exp_f32_e32 v25, v25
	v_and_b32_e32 v26, 0xffff0000, v29
	v_lshlrev_b32_e32 v33, 16, v29
	v_pk_add_f32 v[24:25], v[24:25], 1.0 op_sel_hi:[1,0]
	s_nop 0
	v_div_scale_f32 v27, s[20:21], v25, v25, v26
	v_rcp_f32_e32 v29, v27
	s_nop 0
	v_fma_f32 v36, -v27, v29, 1.0
	v_fmac_f32_e32 v29, v36, v29
	v_div_scale_f32 v36, vcc, v26, v25, v26
	v_mul_f32_e32 v37, v36, v29
	v_fma_f32 v38, -v27, v37, v36
	v_fmac_f32_e32 v37, v38, v29
	v_fma_f32 v27, -v27, v37, v36
	v_div_fmas_f32 v27, v27, v29, v37
	v_div_fixup_f32 v25, v27, v25, v26
	v_div_scale_f32 v26, s[20:21], v24, v24, v33
	v_rcp_f32_e32 v27, v26
	s_nop 0
	v_fma_f32 v29, -v26, v27, 1.0
	v_fmac_f32_e32 v27, v29, v27
	v_div_scale_f32 v29, vcc, v33, v24, v33
	v_mul_f32_e32 v36, v29, v27
	v_fma_f32 v37, -v26, v36, v29
	v_fmac_f32_e32 v36, v37, v27
	v_fma_f32 v26, -v26, v36, v29
	v_div_fmas_f32 v26, v26, v27, v36
	v_div_fixup_f32 v26, v26, v24, v33
	v_cvt_pk_bf16_f32 v24, v32, v28
	v_cvt_pk_bf16_f32 v25, v26, v25
	global_store_dwordx2 v[30:31], v[24:25], off offset:32
	v_mov_b32_e32 v24, v242
	v_mov_b32_e32 v25, v243
	v_lshlrev_b32_e32 v26, 16, v24
	v_and_b32_e32 v24, 0xffff0000, v24
	v_div_scale_f32 v27, s[20:21], v21, v21, v24
	v_rcp_f32_e32 v28, v27
	s_nop 0
	v_fma_f32 v29, -v27, v28, 1.0
	v_fmac_f32_e32 v28, v29, v28
	v_div_scale_f32 v29, vcc, v24, v21, v24
	v_mul_f32_e32 v32, v29, v28
	v_fma_f32 v33, -v27, v32, v29
	v_fmac_f32_e32 v32, v33, v28
	v_fma_f32 v27, -v27, v32, v29
	v_div_fmas_f32 v27, v27, v28, v32
	v_div_fixup_f32 v24, v27, v21, v24
	v_div_scale_f32 v21, s[20:21], v20, v20, v26
	v_rcp_f32_e32 v27, v21
	s_nop 0
	v_fma_f32 v28, -v21, v27, 1.0
	v_fmac_f32_e32 v27, v28, v27
	v_div_scale_f32 v28, vcc, v26, v20, v26
	v_mul_f32_e32 v29, v28, v27
	v_fma_f32 v32, -v21, v29, v28
	v_fmac_f32_e32 v29, v32, v27
	v_fma_f32 v21, -v21, v29, v28
	v_div_fmas_f32 v21, v21, v27, v29
	v_div_fixup_f32 v26, v21, v20, v26
	v_mul_f32_e32 v20, 0xbfb8aa3b, v22
	v_mul_f32_e32 v21, 0xbfb8aa3b, v23
	v_exp_f32_e32 v20, v20
	v_exp_f32_e32 v21, v21
	v_and_b32_e32 v22, 0xffff0000, v25
	v_lshlrev_b32_e32 v27, 16, v25
	v_pk_add_f32 v[20:21], v[20:21], 1.0 op_sel_hi:[1,0]
	s_nop 0
	v_div_scale_f32 v23, s[20:21], v21, v21, v22
	v_rcp_f32_e32 v25, v23
	s_nop 0
	v_fma_f32 v28, -v23, v25, 1.0
	v_fmac_f32_e32 v25, v28, v25
	v_div_scale_f32 v28, vcc, v22, v21, v22
	v_mul_f32_e32 v29, v28, v25
	v_fma_f32 v32, -v23, v29, v28
	v_fmac_f32_e32 v29, v32, v25
	v_fma_f32 v23, -v23, v29, v28
	v_div_fmas_f32 v23, v23, v25, v29
	v_div_fixup_f32 v21, v23, v21, v22
	v_div_scale_f32 v22, s[20:21], v20, v20, v27
	v_rcp_f32_e32 v23, v22
	s_nop 0
	v_fma_f32 v25, -v22, v23, 1.0
	v_fmac_f32_e32 v23, v25, v23
	v_div_scale_f32 v25, vcc, v27, v20, v27
	v_mul_f32_e32 v28, v25, v23
	v_fma_f32 v29, -v22, v28, v25
	v_fmac_f32_e32 v28, v29, v23
	v_fma_f32 v22, -v22, v28, v25
	v_div_fmas_f32 v22, v22, v23, v28
	v_div_fixup_f32 v22, v22, v20, v27
	v_cvt_pk_bf16_f32 v20, v26, v24
	v_cvt_pk_bf16_f32 v21, v22, v21
	global_store_dwordx2 v[30:31], v[20:21], off offset:64
	v_mov_b32_e32 v20, v244
	v_mov_b32_e32 v21, v245
	v_lshlrev_b32_e32 v22, 16, v20
	v_and_b32_e32 v20, 0xffff0000, v20
	v_div_scale_f32 v23, s[20:21], v17, v17, v20
	v_rcp_f32_e32 v24, v23
	s_nop 0
	v_fma_f32 v25, -v23, v24, 1.0
	v_fmac_f32_e32 v24, v25, v24
	v_div_scale_f32 v25, vcc, v20, v17, v20
	v_mul_f32_e32 v26, v25, v24
	v_fma_f32 v27, -v23, v26, v25
	v_fmac_f32_e32 v26, v27, v24
	v_fma_f32 v23, -v23, v26, v25
	v_div_fmas_f32 v23, v23, v24, v26
	v_div_fixup_f32 v20, v23, v17, v20
	v_div_scale_f32 v17, s[20:21], v16, v16, v22
	v_rcp_f32_e32 v23, v17
	s_nop 0
	v_fma_f32 v24, -v17, v23, 1.0
	v_fmac_f32_e32 v23, v24, v23
	v_div_scale_f32 v24, vcc, v22, v16, v22
	v_mul_f32_e32 v25, v24, v23
	v_fma_f32 v26, -v17, v25, v24
	v_fmac_f32_e32 v25, v26, v23
	v_fma_f32 v17, -v17, v25, v24
	v_div_fmas_f32 v17, v17, v23, v25
	v_div_fixup_f32 v22, v17, v16, v22
	v_mul_f32_e32 v16, 0xbfb8aa3b, v18
	v_mul_f32_e32 v17, 0xbfb8aa3b, v19
	v_exp_f32_e32 v16, v16
	v_exp_f32_e32 v17, v17
	v_and_b32_e32 v18, 0xffff0000, v21
	v_lshlrev_b32_e32 v23, 16, v21
	v_pk_add_f32 v[16:17], v[16:17], 1.0 op_sel_hi:[1,0]
	s_nop 0
	v_div_scale_f32 v19, s[20:21], v17, v17, v18
	v_rcp_f32_e32 v21, v19
	s_nop 0
	v_fma_f32 v24, -v19, v21, 1.0
	v_fmac_f32_e32 v21, v24, v21
	v_div_scale_f32 v24, vcc, v18, v17, v18
	v_mul_f32_e32 v25, v24, v21
	v_fma_f32 v26, -v19, v25, v24
	v_fmac_f32_e32 v25, v26, v21
	v_fma_f32 v19, -v19, v25, v24
	v_div_fmas_f32 v19, v19, v21, v25
	v_div_fixup_f32 v17, v19, v17, v18
	v_div_scale_f32 v18, s[20:21], v16, v16, v23
	v_rcp_f32_e32 v19, v18
	s_nop 0
	v_fma_f32 v21, -v18, v19, 1.0
	v_fmac_f32_e32 v19, v21, v19
	v_div_scale_f32 v21, vcc, v23, v16, v23
	v_mul_f32_e32 v24, v21, v19
	v_fma_f32 v25, -v18, v24, v21
	v_fmac_f32_e32 v24, v25, v19
	v_fma_f32 v18, -v18, v24, v21
	v_div_fmas_f32 v18, v18, v19, v24
	v_div_fixup_f32 v18, v18, v16, v23
	v_cvt_pk_bf16_f32 v16, v22, v20
	v_cvt_pk_bf16_f32 v17, v18, v17
	global_store_dwordx2 v[30:31], v[16:17], off offset:96
	v_or_b32_e32 v16, v132, v142
	v_ashrrev_i32_e32 v17, 31, v16
	v_lshlrev_b64 v[18:19], 10, v[16:17]
	v_lshl_add_u64 v[18:19], v[118:119], 0, v[18:19]
	v_mov_b32_e32 v20, v246
	v_mov_b32_e32 v21, v247
	v_lshlrev_b32_e32 v22, 16, v20
	v_and_b32_e32 v20, 0xffff0000, v20
; DI unsigned pack2bf(float a, float b) { const f2_t v = {a, b}; return __builtin_bit_cast(unsigned, __builtin_convertvector(v, bf2_t)); }
; DI void phase5(const Params& P, char* smem) {
;     ...
;     gemm_tile<true>(Yb + (long)brow * 512, 512, WgT + (long)bcol * 512, 512, 0, 8, 0, 0, smem, [&](int row, int col0, f32x4 v) {
;       const long r = brow + row; const int c = bcol + col0;
;       const uint2 yy = *reinterpret_cast<const uint2*>(Yb + r * 512 + c);
;       const float o0 = __uint_as_float(yy.x << 16) / (1.f + __expf(-v[0])), o1 = __uint_as_float(yy.x & 0xffff0000u) / (1.f + __expf(-v[1]));
;       const float o2 = __uint_as_float(yy.y << 16) / (1.f + __expf(-v[2])), o3 = __uint_as_float(yy.y & 0xffff0000u) / (1.f + __expf(-v[3]));
;       *reinterpret_cast<uint2*>(cat + r * 1024 + c) = make_uint2(pack2bf(o0, o1), pack2bf(o2, o3));
	v_div_scale_f32 v23, s[20:21], v13, v13, v20
	v_rcp_f32_e32 v24, v23
	s_nop 0
	v_fma_f32 v25, -v23, v24, 1.0
	v_fmac_f32_e32 v24, v25, v24
	v_div_scale_f32 v25, vcc, v20, v13, v20
	v_mul_f32_e32 v26, v25, v24
	v_fma_f32 v27, -v23, v26, v25
	v_fmac_f32_e32 v26, v27, v24
	v_fma_f32 v23, -v23, v26, v25
	v_div_fmas_f32 v23, v23, v24, v26
	v_div_fixup_f32 v20, v23, v13, v20
	v_div_scale_f32 v13, s[20:21], v12, v12, v22
	v_rcp_f32_e32 v23, v13
	s_nop 0
	v_fma_f32 v24, -v13, v23, 1.0
	v_fmac_f32_e32 v23, v24, v23
	v_div_scale_f32 v24, vcc, v22, v12, v22
	v_mul_f32_e32 v25, v24, v23
	v_fma_f32 v26, -v13, v25, v24
	v_fmac_f32_e32 v25, v26, v23
	v_fma_f32 v13, -v13, v25, v24
	v_div_fmas_f32 v13, v13, v23, v25
	v_div_fixup_f32 v22, v13, v12, v22
	v_mul_f32_e32 v12, 0xbfb8aa3b, v14
	v_mul_f32_e32 v13, 0xbfb8aa3b, v15
	v_exp_f32_e32 v12, v12
	v_exp_f32_e32 v13, v13
	v_and_b32_e32 v14, 0xffff0000, v21
	v_lshlrev_b32_e32 v23, 16, v21
	v_pk_add_f32 v[12:13], v[12:13], 1.0 op_sel_hi:[1,0]
	s_nop 0
	v_div_scale_f32 v15, s[20:21], v13, v13, v14
	v_rcp_f32_e32 v21, v15
	s_nop 0
	v_fma_f32 v24, -v15, v21, 1.0
	v_fmac_f32_e32 v21, v24, v21
	v_div_scale_f32 v24, vcc, v14, v13, v14
	v_mul_f32_e32 v25, v24, v21
	v_fma_f32 v26, -v15, v25, v24
	v_fmac_f32_e32 v25, v26, v21
	v_fma_f32 v15, -v15, v25, v24
	v_div_fmas_f32 v15, v15, v21, v25
	v_div_fixup_f32 v13, v15, v13, v14
	v_div_scale_f32 v14, s[20:21], v12, v12, v23
	v_rcp_f32_e32 v15, v14
	s_nop 0
	v_fma_f32 v21, -v14, v15, 1.0
	v_fmac_f32_e32 v15, v21, v15
	v_div_scale_f32 v21, vcc, v23, v12, v23
	v_mul_f32_e32 v24, v21, v15
	v_fma_f32 v25, -v14, v24, v21
	v_fmac_f32_e32 v24, v25, v15
	v_fma_f32 v14, -v14, v24, v21
	v_div_fmas_f32 v14, v14, v15, v24
	v_div_fixup_f32 v14, v14, v12, v23
	v_cvt_pk_bf16_f32 v13, v14, v13
	v_lshlrev_b64 v[14:15], 11, v[16:17]
	v_cvt_pk_bf16_f32 v12, v22, v20
	v_lshl_add_u64 v[14:15], v[120:121], 0, v[14:15]
	global_store_dwordx2 v[14:15], v[12:13], off
	v_mov_b32_e32 v12, v248
	v_mov_b32_e32 v13, v249
	v_lshlrev_b32_e32 v16, 16, v12
	v_and_b32_e32 v12, 0xffff0000, v12
	v_div_scale_f32 v17, s[20:21], v9, v9, v12
	v_rcp_f32_e32 v20, v17
	s_nop 0
	v_fma_f32 v21, -v17, v20, 1.0
	v_fmac_f32_e32 v20, v21, v20
	v_div_scale_f32 v21, vcc, v12, v9, v12
	v_mul_f32_e32 v22, v21, v20
	v_fma_f32 v23, -v17, v22, v21
	v_fmac_f32_e32 v22, v23, v20
	v_fma_f32 v17, -v17, v22, v21
	v_div_fmas_f32 v17, v17, v20, v22
	v_div_fixup_f32 v12, v17, v9, v12
	v_div_scale_f32 v9, s[20:21], v8, v8, v16
	v_rcp_f32_e32 v17, v9
	s_nop 0
	v_fma_f32 v20, -v9, v17, 1.0
	v_fmac_f32_e32 v17, v20, v17
	v_div_scale_f32 v20, vcc, v16, v8, v16
	v_mul_f32_e32 v21, v20, v17
	v_fma_f32 v22, -v9, v21, v20
	v_fmac_f32_e32 v21, v22, v17
	v_fma_f32 v9, -v9, v21, v20
	v_div_fmas_f32 v9, v9, v17, v21
	v_div_fixup_f32 v16, v9, v8, v16
	v_mul_f32_e32 v8, 0xbfb8aa3b, v10
	v_mul_f32_e32 v9, 0xbfb8aa3b, v11
	v_exp_f32_e32 v8, v8
	v_exp_f32_e32 v9, v9
	v_and_b32_e32 v10, 0xffff0000, v13
	v_lshlrev_b32_e32 v17, 16, v13
	v_pk_add_f32 v[8:9], v[8:9], 1.0 op_sel_hi:[1,0]
	s_nop 0
	v_div_scale_f32 v11, s[20:21], v9, v9, v10
	v_rcp_f32_e32 v13, v11
	s_nop 0
	v_fma_f32 v20, -v11, v13, 1.0
	v_fmac_f32_e32 v13, v20, v13
	v_div_scale_f32 v20, vcc, v10, v9, v10
	v_mul_f32_e32 v21, v20, v13
	v_fma_f32 v22, -v11, v21, v20
	v_fmac_f32_e32 v21, v22, v13
	v_fma_f32 v11, -v11, v21, v20
	v_div_fmas_f32 v11, v11, v13, v21
	v_div_fixup_f32 v9, v11, v9, v10
	v_div_scale_f32 v10, s[20:21], v8, v8, v17
	v_rcp_f32_e32 v11, v10
	s_nop 0
	v_fma_f32 v13, -v10, v11, 1.0
	v_fmac_f32_e32 v11, v13, v11
	v_div_scale_f32 v13, vcc, v17, v8, v17
	v_mul_f32_e32 v20, v13, v11
	v_fma_f32 v21, -v10, v20, v13
	v_fmac_f32_e32 v20, v21, v11
	v_fma_f32 v10, -v10, v20, v13
	v_div_fmas_f32 v10, v10, v11, v20
	v_div_fixup_f32 v10, v10, v8, v17
	v_cvt_pk_bf16_f32 v8, v16, v12
; DI unsigned pack2bf(float a, float b) { const f2_t v = {a, b}; return __builtin_bit_cast(unsigned, __builtin_convertvector(v, bf2_t)); }
; #define TILE_LOOP(tile, N, C)                                                                                          \
;   for (int q0_ = (RBLK >> 3) * 2, tile = 0;                                                                            \
;        q0_ < (N) / 8 && ((tile = xcd_tile((q0_ + VHALF < (N) / 8 ? q0_ + VHALF : q0_), RBLK & 7, (C))), true);          \
;        q0_ += (RGRID >> 3) * 2)
; DI void phase5(const Params& P, char* smem) {
;     ...
;   TILE_LOOP(tile, 256 * 4, 4) {
;     ...
;     gemm_tile<true>(Yb + (long)brow * 512, 512, WgT + (long)bcol * 512, 512, 0, 8, 0, 0, smem, [&](int row, int col0, f32x4 v) {
;       const long r = brow + row; const int c = bcol + col0;
;       const uint2 yy = *reinterpret_cast<const uint2*>(Yb + r * 512 + c);
;       const float o0 = __uint_as_float(yy.x << 16) / (1.f + __expf(-v[0])), o1 = __uint_as_float(yy.x & 0xffff0000u) / (1.f + __expf(-v[1]));
;       const float o2 = __uint_as_float(yy.y << 16) / (1.f + __expf(-v[2])), o3 = __uint_as_float(yy.y & 0xffff0000u) / (1.f + __expf(-v[3]));
;       *reinterpret_cast<uint2*>(cat + r * 1024 + c) = make_uint2(pack2bf(o0, o1), pack2bf(o2, o3));
;     });
	v_cvt_pk_bf16_f32 v9, v10, v9
	global_store_dwordx2 v[14:15], v[8:9], off offset:32
	v_mov_b32_e32 v8, v250
	v_mov_b32_e32 v9, v251
	v_lshlrev_b32_e32 v10, 16, v8
	v_and_b32_e32 v8, 0xffff0000, v8
	v_div_scale_f32 v11, s[20:21], v5, v5, v8
	v_rcp_f32_e32 v12, v11
	s_nop 0
	v_fma_f32 v13, -v11, v12, 1.0
	v_fmac_f32_e32 v12, v13, v12
	v_div_scale_f32 v13, vcc, v8, v5, v8
	v_mul_f32_e32 v16, v13, v12
	v_fma_f32 v17, -v11, v16, v13
	v_fmac_f32_e32 v16, v17, v12
	v_fma_f32 v11, -v11, v16, v13
	v_div_fmas_f32 v11, v11, v12, v16
	v_div_fixup_f32 v8, v11, v5, v8
	v_div_scale_f32 v5, s[20:21], v4, v4, v10
	v_rcp_f32_e32 v11, v5
	s_nop 0
	v_fma_f32 v12, -v5, v11, 1.0
	v_fmac_f32_e32 v11, v12, v11
	v_div_scale_f32 v12, vcc, v10, v4, v10
	v_mul_f32_e32 v13, v12, v11
	v_fma_f32 v16, -v5, v13, v12
	v_fmac_f32_e32 v13, v16, v11
	v_fma_f32 v5, -v5, v13, v12
	v_div_fmas_f32 v5, v5, v11, v13
	v_div_fixup_f32 v10, v5, v4, v10
	v_mul_f32_e32 v4, 0xbfb8aa3b, v6
	v_mul_f32_e32 v5, 0xbfb8aa3b, v7
	v_exp_f32_e32 v4, v4
	v_exp_f32_e32 v5, v5
	v_and_b32_e32 v6, 0xffff0000, v9
	v_lshlrev_b32_e32 v11, 16, v9
	v_pk_add_f32 v[4:5], v[4:5], 1.0 op_sel_hi:[1,0]
	s_nop 0
	v_div_scale_f32 v7, s[20:21], v5, v5, v6
	v_rcp_f32_e32 v9, v7
	s_nop 0
	v_fma_f32 v12, -v7, v9, 1.0
	v_fmac_f32_e32 v9, v12, v9
	v_div_scale_f32 v12, vcc, v6, v5, v6
	v_mul_f32_e32 v13, v12, v9
	v_fma_f32 v16, -v7, v13, v12
	v_fmac_f32_e32 v13, v16, v9
	v_fma_f32 v7, -v7, v13, v12
	v_div_fmas_f32 v7, v7, v9, v13
	v_div_fixup_f32 v5, v7, v5, v6
	v_div_scale_f32 v6, s[20:21], v4, v4, v11
	v_rcp_f32_e32 v7, v6
	s_nop 0
	v_fma_f32 v9, -v6, v7, 1.0
	v_fmac_f32_e32 v7, v9, v7
	v_div_scale_f32 v9, vcc, v11, v4, v11
	v_mul_f32_e32 v12, v9, v7
	v_fma_f32 v13, -v6, v12, v9
	v_fmac_f32_e32 v12, v13, v7
	v_fma_f32 v6, -v6, v12, v9
	v_div_fmas_f32 v6, v6, v7, v12
	v_div_fixup_f32 v6, v6, v4, v11
	v_cvt_pk_bf16_f32 v4, v10, v8
	v_cvt_pk_bf16_f32 v5, v6, v5
	global_store_dwordx2 v[14:15], v[4:5], off offset:64
	v_mov_b32_e32 v4, v252
	v_mov_b32_e32 v5, v253
	v_lshlrev_b32_e32 v6, 16, v4
	v_and_b32_e32 v4, 0xffff0000, v4
	v_div_scale_f32 v7, s[20:21], v1, v1, v4
	v_rcp_f32_e32 v8, v7
	s_nop 0
	v_fma_f32 v9, -v7, v8, 1.0
	v_fmac_f32_e32 v8, v9, v8
	v_div_scale_f32 v9, vcc, v4, v1, v4
	v_mul_f32_e32 v10, v9, v8
	v_fma_f32 v11, -v7, v10, v9
	v_fmac_f32_e32 v10, v11, v8
	v_fma_f32 v7, -v7, v10, v9
	v_div_fmas_f32 v7, v7, v8, v10
	v_div_fixup_f32 v4, v7, v1, v4
	v_div_scale_f32 v1, s[20:21], v0, v0, v6
	v_rcp_f32_e32 v7, v1
	s_nop 0
	v_fma_f32 v8, -v1, v7, 1.0
	v_fmac_f32_e32 v7, v8, v7
	v_div_scale_f32 v8, vcc, v6, v0, v6
	v_mul_f32_e32 v9, v8, v7
	v_fma_f32 v10, -v1, v9, v8
	v_fmac_f32_e32 v9, v10, v7
	v_fma_f32 v1, -v1, v9, v8
	v_div_fmas_f32 v1, v1, v7, v9
	v_div_fixup_f32 v6, v1, v0, v6
	v_mul_f32_e32 v0, 0xbfb8aa3b, v2
	v_mul_f32_e32 v1, 0xbfb8aa3b, v3
	v_exp_f32_e32 v0, v0
	v_exp_f32_e32 v1, v1
	v_and_b32_e32 v2, 0xffff0000, v5
	v_lshlrev_b32_e32 v7, 16, v5
	v_pk_add_f32 v[0:1], v[0:1], 1.0 op_sel_hi:[1,0]
	s_nop 0
	v_div_scale_f32 v3, s[20:21], v1, v1, v2
	v_rcp_f32_e32 v5, v3
	s_nop 0
	v_fma_f32 v8, -v3, v5, 1.0
	v_fmac_f32_e32 v5, v8, v5
	v_div_scale_f32 v8, vcc, v2, v1, v2
	v_mul_f32_e32 v9, v8, v5
	v_fma_f32 v10, -v3, v9, v8
	v_fmac_f32_e32 v9, v10, v5
	v_fma_f32 v3, -v3, v9, v8
	v_div_fmas_f32 v3, v3, v5, v9
	v_div_fixup_f32 v1, v3, v1, v2
	v_div_scale_f32 v2, s[20:21], v0, v0, v7
	v_rcp_f32_e32 v3, v2
	s_nop 0
	v_fma_f32 v5, -v2, v3, 1.0
	v_fmac_f32_e32 v3, v5, v3
	v_div_scale_f32 v5, vcc, v7, v0, v7
	v_mul_f32_e32 v8, v5, v3
	v_fma_f32 v9, -v2, v8, v5
	v_fmac_f32_e32 v8, v9, v3
	v_fma_f32 v2, -v2, v8, v5
	v_div_fmas_f32 v2, v2, v3, v8
	v_div_fixup_f32 v2, v2, v0, v7
	v_cvt_pk_bf16_f32 v0, v6, v4
	v_cvt_pk_bf16_f32 v1, v2, v1
	global_store_dwordx2 v[14:15], v[0:1], off offset:96
	s_cbranch_scc1 .LBB0_874
